# adds batched barrier census loads, hoisted gates-tail constants, hoisted attention-epilogue gain loads, software-pipelined DeltaNet conv loads
# speedup vs baseline: 1.1297x; 1.0057x over previous
; __device__ __forceinline__ float bflo(unsigned w) { return __uint_as_float(w << 16); }
; __device__ __forceinline__ float bfhi(unsigned w) { return __uint_as_float(w & 0xffff0000u); }
; __device__ __forceinline__ void phase_dnprep(ArgsRef a, const Tb tb, int l, LAS unsigned char* lds) {
;     ...
;         {
;             const int row = tid >> 3, seg = tid & 7, cb = seg * 16;
;             const float gci = gcs[row], bi = betas[row], eg = __expf(gci), egl = __expf(gcs[63] - gci);
;             float val[3][16];
; #pragma unroll
;             for (int part = 0; part < 3; ++part) {
;                 const int col0 = part * 512 + h * 128 + cb;
; #pragma unroll
;                 for (int c = 0; c < 16; ++c) val[part][c] = 0.f;
; #pragma unroll
;                 for (int j = 0; j < 4; ++j) {
;                     const int srow = n * 64 + row - 3 + j;
;                     if (srow >= 0) {
;                         const bf16_t* xp = PC + ((size_t)b * SEQ_ + srow) * 1536 + col0;
;                         const u32x4 x0 = *(const u32x4*)xp, x1 = *(const u32x4*)(xp + 8);
;                         const float* wp = convw + j * 1536 + col0;
; #pragma unroll
;                         for (int c4 = 0; c4 < 4; ++c4) {
;                             const f32x4 w4 = *(const f32x4*)(wp + 4 * c4);
;                             const unsigned xa = c4 < 2 ? x0[2 * c4] : x1[2 * (c4 - 2)], xb = c4 < 2 ? x0[2 * c4 + 1] : x1[2 * (c4 - 2) + 1];
;                             val[part][4 * c4 + 0] += w4[0] * bflo(xa); val[part][4 * c4 + 1] += w4[1] * bfhi(xa);
;                             val[part][4 * c4 + 2] += w4[2] * bflo(xb); val[part][4 * c4 + 3] += w4[3] * bfhi(xb);
;                         }
;                     }
;                 }
; #pragma unroll
;                 for (int c = 0; c < 16; ++c) { const float x = val[part][c]; val[part][c] = x * __builtin_amdgcn_rcpf(1.f + __expf(-x)); }
;             }
.LBB0_1028:
	s_or_b64 exec, exec, s[18:19]
	s_waitcnt lgkmcnt(0)
	s_barrier
	ds_read2st64_b32 v[0:1], v80 offset0:64 offset1:65
	ds_read_b32 v116, v181 offset:16636
	v_lshl_or_b32 v62, s33, 7, v79
	v_lshlrev_b32_e32 v180, 1, v62
	v_lshl_add_u64 v[42:43], s[92:93], 0, v[180:181]
	v_lshlrev_b32_e32 v180, 2, v62
	v_add_u32_e32 v34, s29, v81
	v_lshl_add_u64 v[58:59], s[4:5], 0, v[180:181]
	v_mov_b32_e32 v180, v181
	v_cmp_lt_i32_e64 s[80:81], -1, v34
	v_mov_b64_e32 v[14:15], v[180:181]
	v_mov_b64_e32 v[6:7], v[180:181]
	v_mov_b64_e32 v[4:5], v[180:181]
	v_mov_b64_e32 v[2:3], v[180:181]
	v_mov_b64_e32 v[8:9], v[180:181]
	v_mov_b64_e32 v[10:11], v[180:181]
	v_mov_b64_e32 v[12:13], v[180:181]
	v_mov_b64_e32 v[32:33], v[180:181]
	v_cmp_lt_i32_e64 s[82:83], -2, v34
	v_cmp_lt_i32_e64 s[76:77], -3, v34
	v_cmp_lt_i32_e64 s[74:75], -4, v34
	s_movk_i32 s29, 0xc00
	v_max_i32_e32 v36, 0, v34
	v_add_u32_e32 v36, s16, v36
	v_add_u32_e32 v37, 1, v34
	v_max_i32_e32 v37, 0, v37
	v_add_u32_e32 v37, s16, v37
	v_add_u32_e32 v38, 2, v34
	v_max_i32_e32 v38, 0, v38
	v_add_u32_e32 v38, s16, v38
	v_add_u32_e32 v39, 3, v34
	v_max_i32_e32 v39, 0, v39
	v_add_u32_e32 v39, s16, v39
	v_mad_u64_u32 v[216:217], vcc, v36, s29, v[42:43]
	v_mad_u64_u32 v[218:219], vcc, v37, s29, v[42:43]
	v_mad_u64_u32 v[220:221], vcc, v38, s29, v[42:43]
	v_mad_u64_u32 v[222:223], vcc, v39, s29, v[42:43]
	v_add_co_u32_e32 v224, vcc, 0x800, v58
	s_nop 1
	v_addc_co_u32_e32 v225, vcc, 0, v59, vcc
	v_add_co_u32_e32 v226, vcc, 0x2000, v58
	s_nop 1
	v_addc_co_u32_e32 v227, vcc, 0, v59, vcc
	v_add_co_u32_e32 v228, vcc, 0x3800, v58
	s_nop 1
	v_addc_co_u32_e32 v229, vcc, 0, v59, vcc
	v_add_co_u32_e32 v230, vcc, 0x5000, v58
	s_nop 1
	v_addc_co_u32_e32 v231, vcc, 0, v59, vcc
	v_mov_b64_e32 v[54:55], v[180:181]
	v_mov_b64_e32 v[52:53], v[180:181]
	v_mov_b64_e32 v[50:51], v[180:181]
	v_mov_b64_e32 v[48:49], v[180:181]
	v_mov_b64_e32 v[46:47], v[180:181]
	v_mov_b64_e32 v[44:45], v[180:181]
	v_mov_b64_e32 v[42:43], v[180:181]
	v_mov_b64_e32 v[56:57], v[180:181]
	v_mov_b64_e32 v[70:71], v[180:181]
	v_mov_b64_e32 v[68:69], v[180:181]
	v_mov_b64_e32 v[66:67], v[180:181]
	v_mov_b64_e32 v[64:65], v[180:181]
	v_mov_b64_e32 v[62:63], v[180:181]
	v_mov_b64_e32 v[58:59], v[180:181]
	v_mov_b64_e32 v[60:61], v[180:181]
	v_mov_b64_e32 v[72:73], v[180:181]
	global_load_dwordx4 v[144:147], v[216:217], off offset:0
	global_load_dwordx4 v[148:151], v[216:217], off offset:16
	global_load_dwordx4 v[152:155], v[224:225], off offset:-2048
	global_load_dwordx4 v[156:159], v[224:225], off offset:-2032
	global_load_dwordx4 v[160:163], v[224:225], off offset:-2016
	global_load_dwordx4 v[164:167], v[224:225], off offset:-2000
	global_load_dwordx4 v[168:171], v[218:219], off offset:0
	global_load_dwordx4 v[172:175], v[218:219], off offset:16
	global_load_dwordx4 v[176:179], v[226:227], off offset:-2048
	global_load_dwordx4 v[204:207], v[226:227], off offset:-2032
	global_load_dwordx4 v[208:211], v[226:227], off offset:-2016
	global_load_dwordx4 v[212:215], v[226:227], off offset:-2000
	s_waitcnt vmcnt(6)
	s_and_saveexec_b64 s[18:19], s[80:81]
	v_lshlrev_b32_e32 v74, 16, v144
	v_and_b32_e32 v75, 0xffff0000, v144
	v_fma_f32 v32, v152, v74, v32
	v_fma_f32 v33, v153, v75, v33
	v_lshlrev_b32_e32 v76, 16, v145
	v_and_b32_e32 v77, 0xffff0000, v145
	v_fma_f32 v12, v154, v76, v12
	v_fma_f32 v13, v155, v77, v13
	v_lshlrev_b32_e32 v74, 16, v146
	v_and_b32_e32 v75, 0xffff0000, v146
	v_fma_f32 v10, v156, v74, v10
	v_fma_f32 v11, v157, v75, v11
	v_lshlrev_b32_e32 v76, 16, v147
	v_and_b32_e32 v77, 0xffff0000, v147
	v_fma_f32 v8, v158, v76, v8
	v_fma_f32 v9, v159, v77, v9
	v_lshlrev_b32_e32 v74, 16, v148
	v_and_b32_e32 v75, 0xffff0000, v148
	v_fma_f32 v2, v160, v74, v2
	v_fma_f32 v3, v161, v75, v3
	v_lshlrev_b32_e32 v76, 16, v149
	v_and_b32_e32 v77, 0xffff0000, v149
	v_fma_f32 v4, v162, v76, v4
	v_fma_f32 v5, v163, v77, v5
	v_lshlrev_b32_e32 v74, 16, v150
	v_and_b32_e32 v75, 0xffff0000, v150
	v_fma_f32 v6, v164, v74, v6
	v_fma_f32 v7, v165, v75, v7
	v_lshlrev_b32_e32 v76, 16, v151
	v_and_b32_e32 v77, 0xffff0000, v151
	v_fma_f32 v14, v166, v76, v14
	v_fma_f32 v15, v167, v77, v15
	s_or_b64 exec, exec, s[18:19]
	global_load_dwordx4 v[144:147], v[220:221], off offset:0
	global_load_dwordx4 v[148:151], v[220:221], off offset:16
	global_load_dwordx4 v[152:155], v[228:229], off offset:-2048
	global_load_dwordx4 v[156:159], v[228:229], off offset:-2032
	global_load_dwordx4 v[160:163], v[228:229], off offset:-2016
	global_load_dwordx4 v[164:167], v[228:229], off offset:-2000
	s_waitcnt vmcnt(6)
	s_and_saveexec_b64 s[18:19], s[82:83]
	v_lshlrev_b32_e32 v74, 16, v168
	v_and_b32_e32 v75, 0xffff0000, v168
	v_fma_f32 v32, v176, v74, v32
	v_fma_f32 v33, v177, v75, v33
	v_lshlrev_b32_e32 v76, 16, v169
	v_and_b32_e32 v77, 0xffff0000, v169
	v_fma_f32 v12, v178, v76, v12
	v_fma_f32 v13, v179, v77, v13
	v_lshlrev_b32_e32 v74, 16, v170
	v_and_b32_e32 v75, 0xffff0000, v170
	v_fma_f32 v10, v204, v74, v10
	v_fma_f32 v11, v205, v75, v11
	v_lshlrev_b32_e32 v76, 16, v171
	v_and_b32_e32 v77, 0xffff0000, v171
	v_fma_f32 v8, v206, v76, v8
	v_fma_f32 v9, v207, v77, v9
	v_lshlrev_b32_e32 v74, 16, v172
	v_and_b32_e32 v75, 0xffff0000, v172
	v_fma_f32 v2, v208, v74, v2
	v_fma_f32 v3, v209, v75, v3
	v_lshlrev_b32_e32 v76, 16, v173
	v_and_b32_e32 v77, 0xffff0000, v173
	v_fma_f32 v4, v210, v76, v4
	v_fma_f32 v5, v211, v77, v5
	v_lshlrev_b32_e32 v74, 16, v174
	v_and_b32_e32 v75, 0xffff0000, v174
	v_fma_f32 v6, v212, v74, v6
	v_fma_f32 v7, v213, v75, v7
	v_lshlrev_b32_e32 v76, 16, v175
	v_and_b32_e32 v77, 0xffff0000, v175
	v_fma_f32 v14, v214, v76, v14
	v_fma_f32 v15, v215, v77, v15
	s_or_b64 exec, exec, s[18:19]
	global_load_dwordx4 v[168:171], v[222:223], off offset:0
	global_load_dwordx4 v[172:175], v[222:223], off offset:16
	global_load_dwordx4 v[176:179], v[230:231], off offset:-2048
	global_load_dwordx4 v[204:207], v[230:231], off offset:-2032
	global_load_dwordx4 v[208:211], v[230:231], off offset:-2016
	global_load_dwordx4 v[212:215], v[230:231], off offset:-2000
	s_waitcnt vmcnt(6)
; __device__ __forceinline__ float bflo(unsigned w) { return __uint_as_float(w << 16); }
; __device__ __forceinline__ float bfhi(unsigned w) { return __uint_as_float(w & 0xffff0000u); }
; __device__ __forceinline__ void phase_dnprep(ArgsRef a, const Tb tb, int l, LAS unsigned char* lds) {
;     ...
;             for (int part = 0; part < 3; ++part) {
;                 const int col0 = part * 512 + h * 128 + cb;
; #pragma unroll
;                 for (int c = 0; c < 16; ++c) val[part][c] = 0.f;
; #pragma unroll
;                 for (int j = 0; j < 4; ++j) {
;                     const int srow = n * 64 + row - 3 + j;
;                     if (srow >= 0) {
;                         const bf16_t* xp = PC + ((size_t)b * SEQ_ + srow) * 1536 + col0;
;                         const u32x4 x0 = *(const u32x4*)xp, x1 = *(const u32x4*)(xp + 8);
;                         const float* wp = convw + j * 1536 + col0;
; #pragma unroll
;                         for (int c4 = 0; c4 < 4; ++c4) {
;                             const f32x4 w4 = *(const f32x4*)(wp + 4 * c4);
;                             const unsigned xa = c4 < 2 ? x0[2 * c4] : x1[2 * (c4 - 2)], xb = c4 < 2 ? x0[2 * c4 + 1] : x1[2 * (c4 - 2) + 1];
;                             val[part][4 * c4 + 0] += w4[0] * bflo(xa); val[part][4 * c4 + 1] += w4[1] * bfhi(xa);
;                             val[part][4 * c4 + 2] += w4[2] * bflo(xb); val[part][4 * c4 + 3] += w4[3] * bfhi(xb);
;                         }
;                     }
;                 }
	s_and_saveexec_b64 s[18:19], s[76:77]
	v_lshlrev_b32_e32 v74, 16, v144
	v_and_b32_e32 v75, 0xffff0000, v144
	v_fma_f32 v32, v152, v74, v32
	v_fma_f32 v33, v153, v75, v33
	v_lshlrev_b32_e32 v76, 16, v145
	v_and_b32_e32 v77, 0xffff0000, v145
	v_fma_f32 v12, v154, v76, v12
	v_fma_f32 v13, v155, v77, v13
	v_lshlrev_b32_e32 v74, 16, v146
	v_and_b32_e32 v75, 0xffff0000, v146
	v_fma_f32 v10, v156, v74, v10
	v_fma_f32 v11, v157, v75, v11
	v_lshlrev_b32_e32 v76, 16, v147
	v_and_b32_e32 v77, 0xffff0000, v147
	v_fma_f32 v8, v158, v76, v8
	v_fma_f32 v9, v159, v77, v9
	v_lshlrev_b32_e32 v74, 16, v148
	v_and_b32_e32 v75, 0xffff0000, v148
	v_fma_f32 v2, v160, v74, v2
	v_fma_f32 v3, v161, v75, v3
	v_lshlrev_b32_e32 v76, 16, v149
	v_and_b32_e32 v77, 0xffff0000, v149
	v_fma_f32 v4, v162, v76, v4
	v_fma_f32 v5, v163, v77, v5
	v_lshlrev_b32_e32 v74, 16, v150
	v_and_b32_e32 v75, 0xffff0000, v150
	v_fma_f32 v6, v164, v74, v6
	v_fma_f32 v7, v165, v75, v7
	v_lshlrev_b32_e32 v76, 16, v151
	v_and_b32_e32 v77, 0xffff0000, v151
	v_fma_f32 v14, v166, v76, v14
	v_fma_f32 v15, v167, v77, v15
	s_or_b64 exec, exec, s[18:19]
	global_load_dwordx4 v[144:147], v[216:217], off offset:1024
	global_load_dwordx4 v[148:151], v[216:217], off offset:1040
	global_load_dwordx4 v[152:155], v[224:225], off offset:0
	global_load_dwordx4 v[156:159], v[224:225], off offset:16
	global_load_dwordx4 v[160:163], v[224:225], off offset:32
	global_load_dwordx4 v[164:167], v[224:225], off offset:48
	s_waitcnt vmcnt(6)
	s_and_saveexec_b64 s[18:19], s[74:75]
	v_lshlrev_b32_e32 v74, 16, v168
	v_and_b32_e32 v75, 0xffff0000, v168
	v_fma_f32 v32, v176, v74, v32
	v_fma_f32 v33, v177, v75, v33
	v_lshlrev_b32_e32 v76, 16, v169
	v_and_b32_e32 v77, 0xffff0000, v169
	v_fma_f32 v12, v178, v76, v12
	v_fma_f32 v13, v179, v77, v13
	v_lshlrev_b32_e32 v74, 16, v170
	v_and_b32_e32 v75, 0xffff0000, v170
	v_fma_f32 v10, v204, v74, v10
	v_fma_f32 v11, v205, v75, v11
	v_lshlrev_b32_e32 v76, 16, v171
	v_and_b32_e32 v77, 0xffff0000, v171
	v_fma_f32 v8, v206, v76, v8
	v_fma_f32 v9, v207, v77, v9
	v_lshlrev_b32_e32 v74, 16, v172
	v_and_b32_e32 v75, 0xffff0000, v172
	v_fma_f32 v2, v208, v74, v2
	v_fma_f32 v3, v209, v75, v3
	v_lshlrev_b32_e32 v76, 16, v173
	v_and_b32_e32 v77, 0xffff0000, v173
	v_fma_f32 v4, v210, v76, v4
	v_fma_f32 v5, v211, v77, v5
	v_lshlrev_b32_e32 v74, 16, v174
	v_and_b32_e32 v75, 0xffff0000, v174
	v_fma_f32 v6, v212, v74, v6
	v_fma_f32 v7, v213, v75, v7
	v_lshlrev_b32_e32 v76, 16, v175
	v_and_b32_e32 v77, 0xffff0000, v175
	v_fma_f32 v14, v214, v76, v14
	v_fma_f32 v15, v215, v77, v15
	s_or_b64 exec, exec, s[18:19]
	global_load_dwordx4 v[168:171], v[218:219], off offset:1024
	global_load_dwordx4 v[172:175], v[218:219], off offset:1040
	global_load_dwordx4 v[176:179], v[226:227], off offset:0
	global_load_dwordx4 v[204:207], v[226:227], off offset:16
	global_load_dwordx4 v[208:211], v[226:227], off offset:32
	global_load_dwordx4 v[212:215], v[226:227], off offset:48
	s_waitcnt vmcnt(6)
	s_and_saveexec_b64 s[18:19], s[80:81]
	v_lshlrev_b32_e32 v74, 16, v144
	v_and_b32_e32 v75, 0xffff0000, v144
	v_fma_f32 v54, v152, v74, v54
	v_fma_f32 v55, v153, v75, v55
	v_lshlrev_b32_e32 v76, 16, v145
	v_and_b32_e32 v77, 0xffff0000, v145
	v_fma_f32 v52, v154, v76, v52
	v_fma_f32 v53, v155, v77, v53
	v_lshlrev_b32_e32 v74, 16, v146
	v_and_b32_e32 v75, 0xffff0000, v146
	v_fma_f32 v50, v156, v74, v50
	v_fma_f32 v51, v157, v75, v51
	v_lshlrev_b32_e32 v76, 16, v147
	v_and_b32_e32 v77, 0xffff0000, v147
	v_fma_f32 v48, v158, v76, v48
	v_fma_f32 v49, v159, v77, v49
	v_lshlrev_b32_e32 v74, 16, v148
	v_and_b32_e32 v75, 0xffff0000, v148
	v_fma_f32 v46, v160, v74, v46
	v_fma_f32 v47, v161, v75, v47
	v_lshlrev_b32_e32 v76, 16, v149
	v_and_b32_e32 v77, 0xffff0000, v149
	v_fma_f32 v44, v162, v76, v44
	v_fma_f32 v45, v163, v77, v45
	v_lshlrev_b32_e32 v74, 16, v150
	v_and_b32_e32 v75, 0xffff0000, v150
	v_fma_f32 v42, v164, v74, v42
	v_fma_f32 v43, v165, v75, v43
	v_lshlrev_b32_e32 v76, 16, v151
	v_and_b32_e32 v77, 0xffff0000, v151
	v_fma_f32 v56, v166, v76, v56
	v_fma_f32 v57, v167, v77, v57
	s_or_b64 exec, exec, s[18:19]
	global_load_dwordx4 v[144:147], v[220:221], off offset:1024
	global_load_dwordx4 v[148:151], v[220:221], off offset:1040
	global_load_dwordx4 v[152:155], v[228:229], off offset:0
	global_load_dwordx4 v[156:159], v[228:229], off offset:16
	global_load_dwordx4 v[160:163], v[228:229], off offset:32
	global_load_dwordx4 v[164:167], v[228:229], off offset:48
	s_waitcnt vmcnt(6)
	s_and_saveexec_b64 s[18:19], s[82:83]
	v_lshlrev_b32_e32 v74, 16, v168
	v_and_b32_e32 v75, 0xffff0000, v168
	v_fma_f32 v54, v176, v74, v54
	v_fma_f32 v55, v177, v75, v55
	v_lshlrev_b32_e32 v76, 16, v169
	v_and_b32_e32 v77, 0xffff0000, v169
	v_fma_f32 v52, v178, v76, v52
	v_fma_f32 v53, v179, v77, v53
	v_lshlrev_b32_e32 v74, 16, v170
	v_and_b32_e32 v75, 0xffff0000, v170
	v_fma_f32 v50, v204, v74, v50
	v_fma_f32 v51, v205, v75, v51
	v_lshlrev_b32_e32 v76, 16, v171
	v_and_b32_e32 v77, 0xffff0000, v171
	v_fma_f32 v48, v206, v76, v48
	v_fma_f32 v49, v207, v77, v49
	v_lshlrev_b32_e32 v74, 16, v172
	v_and_b32_e32 v75, 0xffff0000, v172
	v_fma_f32 v46, v208, v74, v46
	v_fma_f32 v47, v209, v75, v47
	v_lshlrev_b32_e32 v76, 16, v173
	v_and_b32_e32 v77, 0xffff0000, v173
	v_fma_f32 v44, v210, v76, v44
	v_fma_f32 v45, v211, v77, v45
	v_lshlrev_b32_e32 v74, 16, v174
	v_and_b32_e32 v75, 0xffff0000, v174
	v_fma_f32 v42, v212, v74, v42
	v_fma_f32 v43, v213, v75, v43
	v_lshlrev_b32_e32 v76, 16, v175
	v_and_b32_e32 v77, 0xffff0000, v175
	v_fma_f32 v56, v214, v76, v56
	v_fma_f32 v57, v215, v77, v57
	s_or_b64 exec, exec, s[18:19]
	global_load_dwordx4 v[168:171], v[222:223], off offset:1024
	global_load_dwordx4 v[172:175], v[222:223], off offset:1040
	global_load_dwordx4 v[176:179], v[230:231], off offset:0
	global_load_dwordx4 v[204:207], v[230:231], off offset:16
	global_load_dwordx4 v[208:211], v[230:231], off offset:32
	global_load_dwordx4 v[212:215], v[230:231], off offset:48
	s_waitcnt vmcnt(6)
; __device__ __forceinline__ float bflo(unsigned w) { return __uint_as_float(w << 16); }
; __device__ __forceinline__ float bfhi(unsigned w) { return __uint_as_float(w & 0xffff0000u); }
; __device__ __forceinline__ void phase_dnprep(ArgsRef a, const Tb tb, int l, LAS unsigned char* lds) {
;     ...
;             for (int part = 0; part < 3; ++part) {
;                 const int col0 = part * 512 + h * 128 + cb;
; #pragma unroll
;                 for (int c = 0; c < 16; ++c) val[part][c] = 0.f;
; #pragma unroll
;                 for (int j = 0; j < 4; ++j) {
;                     const int srow = n * 64 + row - 3 + j;
;                     if (srow >= 0) {
;                         const bf16_t* xp = PC + ((size_t)b * SEQ_ + srow) * 1536 + col0;
;                         const u32x4 x0 = *(const u32x4*)xp, x1 = *(const u32x4*)(xp + 8);
;                         const float* wp = convw + j * 1536 + col0;
; #pragma unroll
;                         for (int c4 = 0; c4 < 4; ++c4) {
;                             const f32x4 w4 = *(const f32x4*)(wp + 4 * c4);
;                             const unsigned xa = c4 < 2 ? x0[2 * c4] : x1[2 * (c4 - 2)], xb = c4 < 2 ? x0[2 * c4 + 1] : x1[2 * (c4 - 2) + 1];
;                             val[part][4 * c4 + 0] += w4[0] * bflo(xa); val[part][4 * c4 + 1] += w4[1] * bfhi(xa);
;                             val[part][4 * c4 + 2] += w4[2] * bflo(xb); val[part][4 * c4 + 3] += w4[3] * bfhi(xb);
;                         }
;                     }
;                 }
	s_and_saveexec_b64 s[18:19], s[76:77]
	v_lshlrev_b32_e32 v74, 16, v144
	v_and_b32_e32 v75, 0xffff0000, v144
	v_fma_f32 v54, v152, v74, v54
	v_fma_f32 v55, v153, v75, v55
	v_lshlrev_b32_e32 v76, 16, v145
	v_and_b32_e32 v77, 0xffff0000, v145
	v_fma_f32 v52, v154, v76, v52
	v_fma_f32 v53, v155, v77, v53
	v_lshlrev_b32_e32 v74, 16, v146
	v_and_b32_e32 v75, 0xffff0000, v146
	v_fma_f32 v50, v156, v74, v50
	v_fma_f32 v51, v157, v75, v51
	v_lshlrev_b32_e32 v76, 16, v147
	v_and_b32_e32 v77, 0xffff0000, v147
	v_fma_f32 v48, v158, v76, v48
	v_fma_f32 v49, v159, v77, v49
	v_lshlrev_b32_e32 v74, 16, v148
	v_and_b32_e32 v75, 0xffff0000, v148
	v_fma_f32 v46, v160, v74, v46
	v_fma_f32 v47, v161, v75, v47
	v_lshlrev_b32_e32 v76, 16, v149
	v_and_b32_e32 v77, 0xffff0000, v149
	v_fma_f32 v44, v162, v76, v44
	v_fma_f32 v45, v163, v77, v45
	v_lshlrev_b32_e32 v74, 16, v150
	v_and_b32_e32 v75, 0xffff0000, v150
	v_fma_f32 v42, v164, v74, v42
	v_fma_f32 v43, v165, v75, v43
	v_lshlrev_b32_e32 v76, 16, v151
	v_and_b32_e32 v77, 0xffff0000, v151
	v_fma_f32 v56, v166, v76, v56
	v_fma_f32 v57, v167, v77, v57
	s_or_b64 exec, exec, s[18:19]
	global_load_dwordx4 v[144:147], v[216:217], off offset:2048
	global_load_dwordx4 v[148:151], v[216:217], off offset:2064
	global_load_dwordx4 v[152:155], v[224:225], off offset:2048
	global_load_dwordx4 v[156:159], v[224:225], off offset:2064
	global_load_dwordx4 v[160:163], v[224:225], off offset:2080
	global_load_dwordx4 v[164:167], v[224:225], off offset:2096
	s_waitcnt vmcnt(6)
	s_and_saveexec_b64 s[18:19], s[74:75]
	v_lshlrev_b32_e32 v74, 16, v168
	v_and_b32_e32 v75, 0xffff0000, v168
	v_fma_f32 v54, v176, v74, v54
	v_fma_f32 v55, v177, v75, v55
	v_lshlrev_b32_e32 v76, 16, v169
	v_and_b32_e32 v77, 0xffff0000, v169
	v_fma_f32 v52, v178, v76, v52
	v_fma_f32 v53, v179, v77, v53
	v_lshlrev_b32_e32 v74, 16, v170
	v_and_b32_e32 v75, 0xffff0000, v170
	v_fma_f32 v50, v204, v74, v50
	v_fma_f32 v51, v205, v75, v51
	v_lshlrev_b32_e32 v76, 16, v171
	v_and_b32_e32 v77, 0xffff0000, v171
	v_fma_f32 v48, v206, v76, v48
	v_fma_f32 v49, v207, v77, v49
	v_lshlrev_b32_e32 v74, 16, v172
	v_and_b32_e32 v75, 0xffff0000, v172
	v_fma_f32 v46, v208, v74, v46
	v_fma_f32 v47, v209, v75, v47
	v_lshlrev_b32_e32 v76, 16, v173
	v_and_b32_e32 v77, 0xffff0000, v173
	v_fma_f32 v44, v210, v76, v44
	v_fma_f32 v45, v211, v77, v45
	v_lshlrev_b32_e32 v74, 16, v174
	v_and_b32_e32 v75, 0xffff0000, v174
	v_fma_f32 v42, v212, v74, v42
	v_fma_f32 v43, v213, v75, v43
	v_lshlrev_b32_e32 v76, 16, v175
	v_and_b32_e32 v77, 0xffff0000, v175
	v_fma_f32 v56, v214, v76, v56
	v_fma_f32 v57, v215, v77, v57
	s_or_b64 exec, exec, s[18:19]
	global_load_dwordx4 v[168:171], v[218:219], off offset:2048
	global_load_dwordx4 v[172:175], v[218:219], off offset:2064
	global_load_dwordx4 v[176:179], v[226:227], off offset:2048
	global_load_dwordx4 v[204:207], v[226:227], off offset:2064
	global_load_dwordx4 v[208:211], v[226:227], off offset:2080
	global_load_dwordx4 v[212:215], v[226:227], off offset:2096
	s_waitcnt vmcnt(6)
	s_and_saveexec_b64 s[18:19], s[80:81]
	v_lshlrev_b32_e32 v74, 16, v144
	v_and_b32_e32 v75, 0xffff0000, v144
	v_fma_f32 v70, v152, v74, v70
	v_fma_f32 v71, v153, v75, v71
	v_lshlrev_b32_e32 v76, 16, v145
	v_and_b32_e32 v77, 0xffff0000, v145
	v_fma_f32 v68, v154, v76, v68
	v_fma_f32 v69, v155, v77, v69
	v_lshlrev_b32_e32 v74, 16, v146
	v_and_b32_e32 v75, 0xffff0000, v146
	v_fma_f32 v66, v156, v74, v66
	v_fma_f32 v67, v157, v75, v67
	v_lshlrev_b32_e32 v76, 16, v147
	v_and_b32_e32 v77, 0xffff0000, v147
	v_fma_f32 v64, v158, v76, v64
	v_fma_f32 v65, v159, v77, v65
	v_lshlrev_b32_e32 v74, 16, v148
	v_and_b32_e32 v75, 0xffff0000, v148
	v_fma_f32 v62, v160, v74, v62
	v_fma_f32 v63, v161, v75, v63
	v_lshlrev_b32_e32 v76, 16, v149
	v_and_b32_e32 v77, 0xffff0000, v149
	v_fma_f32 v58, v162, v76, v58
	v_fma_f32 v59, v163, v77, v59
	v_lshlrev_b32_e32 v74, 16, v150
	v_and_b32_e32 v75, 0xffff0000, v150
	v_fma_f32 v60, v164, v74, v60
	v_fma_f32 v61, v165, v75, v61
	v_lshlrev_b32_e32 v76, 16, v151
	v_and_b32_e32 v77, 0xffff0000, v151
	v_fma_f32 v72, v166, v76, v72
	v_fma_f32 v73, v167, v77, v73
	s_or_b64 exec, exec, s[18:19]
	global_load_dwordx4 v[144:147], v[220:221], off offset:2048
	global_load_dwordx4 v[148:151], v[220:221], off offset:2064
	global_load_dwordx4 v[152:155], v[228:229], off offset:2048
	global_load_dwordx4 v[156:159], v[228:229], off offset:2064
	global_load_dwordx4 v[160:163], v[228:229], off offset:2080
	global_load_dwordx4 v[164:167], v[228:229], off offset:2096
	s_waitcnt vmcnt(6)
; __device__ __forceinline__ float bflo(unsigned w) { return __uint_as_float(w << 16); }
; __device__ __forceinline__ float bfhi(unsigned w) { return __uint_as_float(w & 0xffff0000u); }
; __device__ __forceinline__ void phase_dnprep(ArgsRef a, const Tb tb, int l, LAS unsigned char* lds) {
;     ...
;             for (int part = 0; part < 3; ++part) {
;                 const int col0 = part * 512 + h * 128 + cb;
; #pragma unroll
;                 for (int c = 0; c < 16; ++c) val[part][c] = 0.f;
; #pragma unroll
;                 for (int j = 0; j < 4; ++j) {
;                     const int srow = n * 64 + row - 3 + j;
;                     if (srow >= 0) {
;                         const bf16_t* xp = PC + ((size_t)b * SEQ_ + srow) * 1536 + col0;
;                         const u32x4 x0 = *(const u32x4*)xp, x1 = *(const u32x4*)(xp + 8);
;                         const float* wp = convw + j * 1536 + col0;
; #pragma unroll
;                         for (int c4 = 0; c4 < 4; ++c4) {
;                             const f32x4 w4 = *(const f32x4*)(wp + 4 * c4);
;                             const unsigned xa = c4 < 2 ? x0[2 * c4] : x1[2 * (c4 - 2)], xb = c4 < 2 ? x0[2 * c4 + 1] : x1[2 * (c4 - 2) + 1];
;                             val[part][4 * c4 + 0] += w4[0] * bflo(xa); val[part][4 * c4 + 1] += w4[1] * bfhi(xa);
;                             val[part][4 * c4 + 2] += w4[2] * bflo(xb); val[part][4 * c4 + 3] += w4[3] * bfhi(xb);
;                         }
;                     }
;                 }
	s_and_saveexec_b64 s[18:19], s[82:83]
	v_lshlrev_b32_e32 v74, 16, v168
	v_and_b32_e32 v75, 0xffff0000, v168
	v_fma_f32 v70, v176, v74, v70
	v_fma_f32 v71, v177, v75, v71
	v_lshlrev_b32_e32 v76, 16, v169
	v_and_b32_e32 v77, 0xffff0000, v169
	v_fma_f32 v68, v178, v76, v68
	v_fma_f32 v69, v179, v77, v69
	v_lshlrev_b32_e32 v74, 16, v170
	v_and_b32_e32 v75, 0xffff0000, v170
	v_fma_f32 v66, v204, v74, v66
	v_fma_f32 v67, v205, v75, v67
	v_lshlrev_b32_e32 v76, 16, v171
	v_and_b32_e32 v77, 0xffff0000, v171
	v_fma_f32 v64, v206, v76, v64
	v_fma_f32 v65, v207, v77, v65
	v_lshlrev_b32_e32 v74, 16, v172
	v_and_b32_e32 v75, 0xffff0000, v172
	v_fma_f32 v62, v208, v74, v62
	v_fma_f32 v63, v209, v75, v63
	v_lshlrev_b32_e32 v76, 16, v173
	v_and_b32_e32 v77, 0xffff0000, v173
	v_fma_f32 v58, v210, v76, v58
	v_fma_f32 v59, v211, v77, v59
	v_lshlrev_b32_e32 v74, 16, v174
	v_and_b32_e32 v75, 0xffff0000, v174
	v_fma_f32 v60, v212, v74, v60
	v_fma_f32 v61, v213, v75, v61
	v_lshlrev_b32_e32 v76, 16, v175
	v_and_b32_e32 v77, 0xffff0000, v175
	v_fma_f32 v72, v214, v76, v72
	v_fma_f32 v73, v215, v77, v73
	s_or_b64 exec, exec, s[18:19]
	global_load_dwordx4 v[168:171], v[222:223], off offset:2048
	global_load_dwordx4 v[172:175], v[222:223], off offset:2064
	global_load_dwordx4 v[176:179], v[230:231], off offset:2048
	global_load_dwordx4 v[204:207], v[230:231], off offset:2064
	global_load_dwordx4 v[208:211], v[230:231], off offset:2080
	global_load_dwordx4 v[212:215], v[230:231], off offset:2096
	s_waitcnt vmcnt(6)
	s_and_saveexec_b64 s[18:19], s[76:77]
	v_lshlrev_b32_e32 v74, 16, v144
	v_and_b32_e32 v75, 0xffff0000, v144
	v_fma_f32 v70, v152, v74, v70
	v_fma_f32 v71, v153, v75, v71
	v_lshlrev_b32_e32 v76, 16, v145
	v_and_b32_e32 v77, 0xffff0000, v145
	v_fma_f32 v68, v154, v76, v68
	v_fma_f32 v69, v155, v77, v69
	v_lshlrev_b32_e32 v74, 16, v146
	v_and_b32_e32 v75, 0xffff0000, v146
	v_fma_f32 v66, v156, v74, v66
	v_fma_f32 v67, v157, v75, v67
	v_lshlrev_b32_e32 v76, 16, v147
	v_and_b32_e32 v77, 0xffff0000, v147
	v_fma_f32 v64, v158, v76, v64
	v_fma_f32 v65, v159, v77, v65
	v_lshlrev_b32_e32 v74, 16, v148
	v_and_b32_e32 v75, 0xffff0000, v148
	v_fma_f32 v62, v160, v74, v62
	v_fma_f32 v63, v161, v75, v63
	v_lshlrev_b32_e32 v76, 16, v149
	v_and_b32_e32 v77, 0xffff0000, v149
	v_fma_f32 v58, v162, v76, v58
	v_fma_f32 v59, v163, v77, v59
	v_lshlrev_b32_e32 v74, 16, v150
	v_and_b32_e32 v75, 0xffff0000, v150
	v_fma_f32 v60, v164, v74, v60
	v_fma_f32 v61, v165, v75, v61
	v_lshlrev_b32_e32 v76, 16, v151
	v_and_b32_e32 v77, 0xffff0000, v151
	v_fma_f32 v72, v166, v76, v72
	v_fma_f32 v73, v167, v77, v73
	s_or_b64 exec, exec, s[18:19]
	s_waitcnt vmcnt(0)
	s_and_saveexec_b64 s[18:19], s[74:75]
	v_lshlrev_b32_e32 v74, 16, v168
	v_and_b32_e32 v75, 0xffff0000, v168
	v_fma_f32 v70, v176, v74, v70
	v_fma_f32 v71, v177, v75, v71
	v_lshlrev_b32_e32 v76, 16, v169
	v_and_b32_e32 v77, 0xffff0000, v169
	v_fma_f32 v68, v178, v76, v68
	v_fma_f32 v69, v179, v77, v69
	v_lshlrev_b32_e32 v74, 16, v170
	v_and_b32_e32 v75, 0xffff0000, v170
	v_fma_f32 v66, v204, v74, v66
	v_fma_f32 v67, v205, v75, v67
	v_lshlrev_b32_e32 v76, 16, v171
	v_and_b32_e32 v77, 0xffff0000, v171
	v_fma_f32 v64, v206, v76, v64
	v_fma_f32 v65, v207, v77, v65
	v_lshlrev_b32_e32 v74, 16, v172
	v_and_b32_e32 v75, 0xffff0000, v172
	v_fma_f32 v62, v208, v74, v62
	v_fma_f32 v63, v209, v75, v63
	v_lshlrev_b32_e32 v76, 16, v173
	v_and_b32_e32 v77, 0xffff0000, v173
	v_fma_f32 v58, v210, v76, v58
	v_fma_f32 v59, v211, v77, v59
	v_lshlrev_b32_e32 v74, 16, v174
	v_and_b32_e32 v75, 0xffff0000, v174
	v_fma_f32 v60, v212, v74, v60
	v_fma_f32 v61, v213, v75, v61
	v_lshlrev_b32_e32 v76, 16, v175
	v_and_b32_e32 v77, 0xffff0000, v175
	v_fma_f32 v72, v214, v76, v72
	v_fma_f32 v73, v215, v77, v73
	s_or_b64 exec, exec, s[18:19]

; __device__ __forceinline__ unsigned pk2(float lo, float hi) { const f32x2_t v = {lo, hi}; const bf16x2_t b = __builtin_convertvector(v, bf16x2_t); return __builtin_bit_cast(unsigned, b); }
; __device__ __forceinline__ int perm32k(int q) { return ((q >> 2) & 3) * 8 + ((q >> 4) & 1) * 4 + (q & 3); }
; __device__ __forceinline__ void phase_dnprep(ArgsRef a, const Tb tb, int l, LAS unsigned char* lds) {
;     ...
;                 const float dec = (row >= col) ? __expf(gcs[row] - gcol) : 0.f;
;                 if (mat == 0) Lm[row * 64 + col] = (col < row) ? betas[row] * cacc[i] * dec : 0.f;
;                 else { const unsigned av = pk2((col <= row) ? cacc[i] * dec : 0.f, 0.f); DA[((size_t)ci * 64 + row) * 64 + (col & 32) + perm32k(col & 31)] = (bf16_t)(av & 0xffff); }
.LBB0_1100:
	s_andn2_saveexec_b64 s[16:17], s[16:17]
	s_cbranch_execnz .LBB0_1179
	s_branch .LBB0_1182
.LBB0_1106:
	v_mul_f32_e32 v0, v0, v37
	v_readlane_b32 s18, v254, 44
	v_cvt_pk_bf16_f32 v0, v0, s0
	v_readlane_b32 s19, v254, 45
	s_nop 1
	v_cndmask_b32_e64 v0, v0, 0, s[18:19]
	global_store_short v[34:35], v0, off offset:-256
	s_andn2_saveexec_b64 s[16:17], s[16:17]
	s_cbranch_execz .LBB0_1053

; __device__ __forceinline__ void phase_gates(ArgsRef a, const Tb tb, int l) {
;     unsigned char* ws = a.ws;
;     const float* wg8 = (const float*)(ws + OFF_WG8);
;     const float* stats = (const float*)(ws + OFF_MUR) + (size_t)(l * 3 + 0) * T_ * 2;
;     float* gates = (float*)(ws + OFF_GATES);
;     const bf16_t* YBp = (const bf16_t*)(ws + OFF_YB);
;     const int wv = tb.tid >> 6, lane = tb.tid & 63;
;     const int gw = tb.bid * 8 + wv, GW = tb.G * 8;
;     for (int t = gw; t < T_; t += GW) {
.LBB0_1185:
	s_and_b64 vcc, exec, s[2:3]
	s_mov_b32 s73, s65
	s_cbranch_vccz .LBB0_1255
	v_readlane_b32 s38, v254, 42
	v_ashrrev_i32_e32 v198, 6, v196
	s_lshl_b32 s16, s38, 3
	s_waitcnt vmcnt(0)
	v_add_u32_e32 v77, s16, v198
	s_movk_i32 s2, 0x4000
	v_cmp_gt_i32_e32 vcc, s2, v77
	v_and_b32_e32 v76, 63, v196
	v_readlane_b32 s39, v254, 43
	s_and_saveexec_b64 s[12:13], vcc
	s_mov_b32 s30, 0x3fb8aa3b
	s_mov_b32 s31, 0x42ce8ed0
	s_mov_b32 s33, 0xc2b17218
	s_mov_b32 s34, 0xc2ce8ed0
	s_mov_b32 s35, 0x42b17218
	s_movk_i32 s36, 0x3fff
	s_mov_b64 s[24:25], 0x3000
	s_mov_b64 s[26:27], 0x2000
	v_readlane_b32 s4, v254, 36
	v_readlane_b32 s40, v254, 40
	v_readlane_b32 s5, v254, 37
	v_readlane_b32 s41, v254, 41
	s_cbranch_execz .LBB0_1195
; __device__ __forceinline__ float bflo(unsigned w) { return __uint_as_float(w << 16); }
; __device__ __forceinline__ float bfhi(unsigned w) { return __uint_as_float(w & 0xffff0000u); }
; __device__ __forceinline__ void phase_gates(ArgsRef a, const Tb tb, int l) {
;     ...
;     const int wv = tb.tid >> 6, lane = tb.tid & 63;
;     const int gw = tb.bid * 8 + wv, GW = tb.G * 8;
;     for (int t = gw; t < T_; t += GW) {
;         f32x4 y[4];
; #pragma unroll
;         for (int i = 0; i < 4; ++i) { const u32x2 rb = *(const u32x2*)(YBp + (size_t)t * D_ + i * 256 + lane * 4); y[i] = (f32x4){bflo(rb.x), bfhi(rb.x), bflo(rb.y), bfhi(rb.y)}; }
;         float mu, rstd; row_stats(stats, t, mu, rstd);
;         float s8[8];
; #pragma unroll
;         for (int j = 0; j < 8; ++j) { float s = 0.f;
; #pragma unroll
;             for (int i = 0; i < 4; ++i) { const f32x4 w = *(const f32x4*)(wg8 + j * 1024 + i * 256 + lane * 4); s += (y[i][0] * w[0] + y[i][1] * w[1]) + (y[i][2] * w[2] + y[i][3] * w[3]); }
;             s8[j] = s; }
;         const bool b5 = (lane & 32) != 0, b4 = (lane & 16) != 0, b3 = (lane & 8) != 0;
;         float r4[4], q2[2];
; #pragma unroll
;         for (int j = 0; j < 4; ++j) { const float keep = b5 ? s8[j + 4] : s8[j], send = b5 ? s8[j] : s8[j + 4]; r4[j] = keep + __shfl_xor(send, 32); }
; #pragma unroll
;         for (int j = 0; j < 2; ++j) { const float keep = b4 ? r4[j + 2] : r4[j], send = b4 ? r4[j] : r4[j + 2]; q2[j] = keep + __shfl_xor(send, 16); }
;         float dv = (b3 ? q2[1] : q2[0]) + __shfl_xor(b3 ? q2[0] : q2[1], 8);
;         dv += __shfl_xor(dv, 4); dv += __shfl_xor(dv, 2); dv += __shfl_xor(dv, 1);
;         if ((lane & 7) == 0) {
;             const int j = lane >> 3;
;             const float v = rstd * (dv - mu * wg8[8192 + j]) + wg8[8192 + 8 + j];
;             float o;
;             if (j < 4) o = 1.f / (1.f + expf(-v));
;             else { const int h = j - 4; const float xx = v + a.in[10][l * 4 + h]; const float sp = fmaxf(xx, 0.f) + log1pf(expf(-fabsf(xx))); o = -expf(a.in[9][l * 4 + h]) * sp; }
	s_lshl_b32 s14, s4, 3
	v_and_b32_e32 v0, 32, v196
	s_waitcnt lgkmcnt(0)
	s_add_u32 s10, s48, 0x2a1d000
	v_cmp_eq_u32_e64 s[2:3], 0, v0
	v_and_b32_e32 v0, 16, v196
	s_addc_u32 s11, s49, 0
	v_lshlrev_b32_e32 v180, 4, v76
	v_cmp_eq_u32_e64 s[4:5], 0, v0
	v_and_b32_e32 v0, 8, v196
	v_lshl_add_u64 v[4:5], s[10:11], 0, v[180:181]
	v_cmp_eq_u32_e64 s[6:7], 0, v0
	v_xor_b32_e32 v0, 32, v236
	s_mov_b64 s[18:19], 0x1000
	v_cmp_lt_i32_e32 vcc, v0, v239
	v_lshl_add_u64 v[14:15], v[4:5], 0, s[18:19]
	s_mov_b64 s[18:19], 0x1400
	v_cndmask_b32_e32 v0, v236, v0, vcc
	v_lshl_add_u64 v[16:17], v[4:5], 0, s[18:19]
	s_mov_b64 s[18:19], 0x1800
	v_lshlrev_b32_e32 v78, 2, v0
	v_xor_b32_e32 v0, 16, v236
	v_lshl_add_u64 v[18:19], v[4:5], 0, s[18:19]
	s_mov_b64 s[18:19], 0x1c00
	v_cmp_lt_i32_e32 vcc, v0, v239
	v_lshl_add_u64 v[20:21], v[4:5], 0, s[18:19]
	s_mov_b64 s[18:19], 0x2400
	v_cndmask_b32_e32 v0, v236, v0, vcc
	v_lshl_add_u64 v[24:25], v[4:5], 0, s[18:19]
	s_mov_b64 s[18:19], 0x2800
	v_lshlrev_b32_e32 v79, 2, v0
	v_xor_b32_e32 v0, 8, v236
	v_lshl_add_u64 v[26:27], v[4:5], 0, s[18:19]
	s_mov_b64 s[18:19], 0x2c00
	v_cmp_lt_i32_e32 vcc, v0, v239
	v_lshl_add_u64 v[28:29], v[4:5], 0, s[18:19]
	s_mov_b64 s[18:19], 0x3400
	v_cndmask_b32_e32 v0, v236, v0, vcc
	v_cmp_lt_i32_e32 vcc, v241, v239
	v_lshl_add_u64 v[32:33], v[4:5], 0, s[18:19]
	s_mov_b64 s[18:19], 0x3800
	v_lshlrev_b32_e32 v80, 2, v0
	v_cndmask_b32_e32 v0, v236, v241, vcc
	v_cmp_lt_i32_e32 vcc, v240, v239
	v_lshl_add_u64 v[34:35], v[4:5], 0, s[18:19]
	s_mov_b64 s[18:19], 0x3c00
	v_lshlrev_b32_e32 v81, 2, v0
	v_cndmask_b32_e32 v0, v236, v240, vcc
	v_cmp_lt_i32_e32 vcc, v237, v239
	v_lshl_add_u64 v[36:37], v[4:5], 0, s[18:19]
	s_mov_b64 s[18:19], 0x4000
	v_lshlrev_b32_e32 v82, 2, v0
	v_cndmask_b32_e32 v0, v236, v237, vcc
	v_lshl_add_u64 v[38:39], v[4:5], 0, s[18:19]
	s_mov_b64 s[18:19], 0x4400
	v_lshlrev_b32_e32 v83, 2, v0
	v_and_b32_e32 v0, 7, v196
	v_lshl_add_u64 v[40:41], v[4:5], 0, s[18:19]
	s_mov_b64 s[18:19], 0x4800
	v_cmp_eq_u32_e64 s[8:9], 0, v0
	v_lshrrev_b32_e32 v0, 1, v76
	v_mov_b32_e32 v1, v181
	v_lshl_add_u64 v[42:43], v[4:5], 0, s[18:19]
	s_mov_b64 s[18:19], 0x4c00
	v_lshl_add_u64 v[0:1], s[10:11], 0, v[0:1]
	s_mov_b64 s[10:11], 0x8000
	v_lshl_add_u64 v[44:45], v[4:5], 0, s[18:19]
	s_mov_b64 s[18:19], 0x5000
	v_lshl_add_u64 v[6:7], v[0:1], 0, s[10:11]
	s_mov_b64 s[10:11], 0x8020
	v_lshl_add_u64 v[46:47], v[4:5], 0, s[18:19]
	s_mov_b64 s[18:19], 0x5400
	v_lshl_add_u64 v[8:9], v[0:1], 0, s[10:11]
	v_readlane_b32 s10, v254, 19
	v_lshl_add_u64 v[48:49], v[4:5], 0, s[18:19]
	s_mov_b64 s[18:19], 0x5800
	v_readlane_b32 s11, v254, 20
	v_lshl_add_u64 v[50:51], v[4:5], 0, s[18:19]
	s_mov_b64 s[18:19], 0x5c00
	s_load_dwordx4 s[20:23], s[10:11], 0x48
	v_lshl_add_u64 v[52:53], v[4:5], 0, s[18:19]
	s_mov_b64 s[18:19], 0x6000
	s_lshl_b32 s10, s40, 2
	v_lshl_add_u64 v[54:55], v[4:5], 0, s[18:19]
	s_mov_b64 s[18:19], 0x6400
	v_lshrrev_b32_e32 v180, 3, v76
	s_ashr_i32 s11, s10, 31
	v_lshl_add_u64 v[56:57], v[4:5], 0, s[18:19]
	s_mov_b64 s[18:19], 0x6800
	v_lshl_add_u64 v[0:1], s[10:11], 0, v[180:181]
	v_lshl_add_u64 v[58:59], v[4:5], 0, s[18:19]
	s_mov_b64 s[18:19], 0x6c00
	v_lshlrev_b64 v[0:1], 2, v[0:1]
	v_lshl_add_u64 v[60:61], v[4:5], 0, s[18:19]
	s_mov_b64 s[18:19], 0x7000
	v_ashrrev_i32_e32 v199, 31, v198
	s_ashr_i32 s17, s16, 31
	s_waitcnt lgkmcnt(0)
	v_lshl_add_u64 v[10:11], s[22:23], 0, v[0:1]
	v_lshl_add_u64 v[12:13], s[20:21], 0, v[0:1]
	v_lshl_add_u64 v[62:63], v[4:5], 0, s[18:19]
	s_mov_b64 s[18:19], 0x7400
	v_lshl_add_u64 v[0:1], v[198:199], 0, s[16:17]
	v_lshl_add_u64 v[64:65], v[4:5], 0, s[18:19]
	s_mov_b64 s[18:19], 0x7800
	v_lshlrev_b64 v[2:3], 5, v[0:1]
	v_lshl_add_u64 v[66:67], v[4:5], 0, s[18:19]
	s_mov_b64 s[18:19], 0x7c00
	v_lshl_add_u64 v[2:3], s[48:49], 0, v[2:3]
	s_mov_b64 s[16:17], 0x36e5040
	s_ashr_i32 s15, s14, 31
	v_lshl_add_u64 v[68:69], v[4:5], 0, s[18:19]
	v_lshl_add_u64 v[70:71], v[2:3], 0, s[16:17]
	s_lshl_b64 s[16:17], s[14:15], 5
	v_readlane_b32 s18, v254, 31
	s_add_u32 s18, s18, s88
	v_readlane_b32 s19, v254, 32
	s_addc_u32 s19, s19, s89
	s_mov_b64 s[20:21], 0x376a500
	v_lshl_add_u64 v[72:73], v[0:1], 3, s[18:19]
	v_lshlrev_b64 v[0:1], 11, v[0:1]
	v_lshl_or_b32 v0, v76, 3, v0
	v_lshl_add_u64 v[0:1], s[48:49], 0, v[0:1]
	v_cmp_lt_u32_e64 s[10:11], 31, v76
	v_lshl_add_u64 v[22:23], v[4:5], 0, s[26:27]
	v_lshl_add_u64 v[30:31], v[4:5], 0, s[24:25]
	s_lshl_b64 s[18:19], s[14:15], 3
	v_lshl_add_u64 v[74:75], v[0:1], 0, s[20:21]
	s_lshl_b64 s[20:21], s[14:15], 11
	s_mov_b64 s[22:23], 0
	global_load_dwordx4 v[108:111], v[4:5], off
	global_load_dwordx4 v[112:115], v[4:5], off offset:1024
	global_load_dwordx4 v[116:119], v[4:5], off offset:2048
	global_load_dwordx4 v[120:123], v[4:5], off offset:3072
	global_load_dwordx4 v[124:127], v[14:15], off
	global_load_dwordx4 v[128:131], v[14:15], off offset:1024
	global_load_dwordx4 v[132:135], v[14:15], off offset:2048
	global_load_dwordx4 v[136:139], v[14:15], off offset:3072
	global_load_dwordx4 v[140:143], v[22:23], off
	global_load_dwordx4 v[144:147], v[22:23], off offset:1024
	global_load_dwordx4 v[148:151], v[22:23], off offset:2048
	global_load_dwordx4 v[152:155], v[22:23], off offset:3072
	global_load_dwordx4 v[156:159], v[30:31], off
	global_load_dwordx4 v[160:163], v[30:31], off offset:1024
	global_load_dwordx4 v[164:167], v[30:31], off offset:2048
	global_load_dwordx4 v[168:171], v[30:31], off offset:3072
	global_load_dwordx4 v[172:175], v[38:39], off
	global_load_dwordx4 v[176:179], v[38:39], off offset:1024
	global_load_dwordx4 v[204:207], v[38:39], off offset:2048
	global_load_dwordx4 v[208:211], v[38:39], off offset:3072
	global_load_dwordx4 v[212:215], v[46:47], off
	global_load_dwordx4 v[216:219], v[46:47], off offset:1024
	global_load_dwordx4 v[220:223], v[46:47], off offset:2048
	global_load_dwordx4 v[224:227], v[46:47], off offset:3072
	global_load_dwordx4 v[228:231], v[54:55], off
	global_load_dwordx4 v[232:235], v[54:55], off offset:1024
	global_load_dwordx4 v[16:19], v[54:55], off offset:2048
	global_load_dwordx4 v[24:27], v[54:55], off offset:3072
	global_load_dwordx4 v[32:35], v[62:63], off
	global_load_dwordx4 v[40:43], v[62:63], off offset:1024
	global_load_dwordx4 v[48:51], v[62:63], off offset:2048
	global_load_dwordx4 v[56:59], v[62:63], off offset:3072
	s_and_saveexec_b64 s[24:25], s[8:9]
	global_load_dword v60, v[6:7], off
	global_load_dword v61, v[8:9], off
	s_and_b64 exec, exec, s[10:11]
	global_load_dword v68, v[10:11], off offset:-16
	global_load_dword v69, v[12:13], off offset:-16
	s_mov_b64 exec, s[24:25]
	s_branch .LBB0_1190

; __device__ __forceinline__ float bflo(unsigned w) { return __uint_as_float(w << 16); }
; __device__ __forceinline__ float bfhi(unsigned w) { return __uint_as_float(w & 0xffff0000u); }
; __device__ __forceinline__ void phase_gates(ArgsRef a, const Tb tb, int l) {
;     ...
;     for (int t = gw; t < T_; t += GW) {
;         f32x4 y[4];
; #pragma unroll
;         for (int i = 0; i < 4; ++i) { const u32x2 rb = *(const u32x2*)(YBp + (size_t)t * D_ + i * 256 + lane * 4); y[i] = (f32x4){bflo(rb.x), bfhi(rb.x), bflo(rb.y), bfhi(rb.y)}; }
;         float mu, rstd; row_stats(stats, t, mu, rstd);
;         float s8[8];
; #pragma unroll
;         for (int j = 0; j < 8; ++j) { float s = 0.f;
; #pragma unroll
;             for (int i = 0; i < 4; ++i) { const f32x4 w = *(const f32x4*)(wg8 + j * 1024 + i * 256 + lane * 4); s += (y[i][0] * w[0] + y[i][1] * w[1]) + (y[i][2] * w[2] + y[i][3] * w[3]); }
;             s8[j] = s; }
.LBB0_1190:
	s_waitcnt lgkmcnt(0)
	global_load_dwordx2 v[0:1], v[74:75], off offset:-1024
	global_load_dwordx2 v[2:3], v[74:75], off offset:-512
	global_load_dwordx2 v[84:85], v[74:75], off
	global_load_dwordx2 v[86:87], v[74:75], off offset:512
	global_load_dwordx2 v[52:53], v[72:73], off
	s_waitcnt vmcnt(0)
	v_lshlrev_b32_e32 v91, 16, v0
	v_and_b32_e32 v92, 0xffff0000, v0
	v_lshlrev_b32_e32 v93, 16, v1
	v_and_b32_e32 v94, 0xffff0000, v1
	v_lshlrev_b32_e32 v95, 16, v2
	v_and_b32_e32 v96, 0xffff0000, v2
	v_lshlrev_b32_e32 v97, 16, v3
	v_and_b32_e32 v98, 0xffff0000, v3
	v_lshlrev_b32_e32 v103, 16, v84
	v_and_b32_e32 v104, 0xffff0000, v84
	v_lshlrev_b32_e32 v105, 16, v85
	v_and_b32_e32 v106, 0xffff0000, v85
	v_lshlrev_b32_e32 v20, 16, v86
	v_and_b32_e32 v21, 0xffff0000, v86
	v_lshlrev_b32_e32 v28, 16, v87
	v_and_b32_e32 v29, 0xffff0000, v87
	v_mul_f32_e32 v36, v109, v92
	v_mul_f32_e32 v37, v111, v94
	v_fmac_f32_e32 v36, v108, v91
	v_fmac_f32_e32 v37, v110, v93
	v_add_f32_e32 v36, v36, v37
	v_add_f32_e32 v88, 0, v36
	v_mul_f32_e32 v44, v113, v96
	v_mul_f32_e32 v45, v115, v98
	v_fmac_f32_e32 v44, v112, v95
	v_fmac_f32_e32 v45, v114, v97
	v_add_f32_e32 v44, v44, v45
	v_add_f32_e32 v88, v88, v44
	v_mul_f32_e32 v36, v117, v104
	v_mul_f32_e32 v37, v119, v106
	v_fmac_f32_e32 v36, v116, v103
	v_fmac_f32_e32 v37, v118, v105
	v_add_f32_e32 v36, v36, v37
	v_add_f32_e32 v88, v88, v36
	v_mul_f32_e32 v44, v121, v21
	v_mul_f32_e32 v45, v123, v29
	v_fmac_f32_e32 v44, v120, v20
	v_fmac_f32_e32 v45, v122, v28
	v_add_f32_e32 v44, v44, v45
	v_add_f32_e32 v88, v88, v44
	v_mul_f32_e32 v36, v125, v92
	v_mul_f32_e32 v37, v127, v94
	v_fmac_f32_e32 v36, v124, v91
	v_fmac_f32_e32 v37, v126, v93
	v_add_f32_e32 v36, v36, v37
	v_add_f32_e32 v89, 0, v36
	v_mul_f32_e32 v44, v129, v96
	v_mul_f32_e32 v45, v131, v98
	v_fmac_f32_e32 v44, v128, v95
	v_fmac_f32_e32 v45, v130, v97
	v_add_f32_e32 v44, v44, v45
	v_add_f32_e32 v89, v89, v44
	v_mul_f32_e32 v36, v133, v104
	v_mul_f32_e32 v37, v135, v106
	v_fmac_f32_e32 v36, v132, v103
	v_fmac_f32_e32 v37, v134, v105
	v_add_f32_e32 v36, v36, v37
	v_add_f32_e32 v89, v89, v36
	v_mul_f32_e32 v44, v137, v21
	v_mul_f32_e32 v45, v139, v29
	v_fmac_f32_e32 v44, v136, v20
	v_fmac_f32_e32 v45, v138, v28
	v_add_f32_e32 v44, v44, v45
	v_add_f32_e32 v89, v89, v44
	v_mul_f32_e32 v36, v141, v92
	v_mul_f32_e32 v37, v143, v94
	v_fmac_f32_e32 v36, v140, v91
	v_fmac_f32_e32 v37, v142, v93
	v_add_f32_e32 v36, v36, v37
	v_add_f32_e32 v90, 0, v36
	v_mul_f32_e32 v44, v145, v96
	v_mul_f32_e32 v45, v147, v98
	v_fmac_f32_e32 v44, v144, v95
	v_fmac_f32_e32 v45, v146, v97
	v_add_f32_e32 v44, v44, v45
	v_add_f32_e32 v90, v90, v44
	v_mul_f32_e32 v36, v149, v104
	v_mul_f32_e32 v37, v151, v106
	v_fmac_f32_e32 v36, v148, v103
	v_fmac_f32_e32 v37, v150, v105
	v_add_f32_e32 v36, v36, v37
	v_add_f32_e32 v90, v90, v36
	v_mul_f32_e32 v44, v153, v21
	v_mul_f32_e32 v45, v155, v29
	v_fmac_f32_e32 v44, v152, v20
	v_fmac_f32_e32 v45, v154, v28
	v_add_f32_e32 v44, v44, v45
	v_add_f32_e32 v90, v90, v44
	v_mul_f32_e32 v36, v157, v92
	v_mul_f32_e32 v37, v159, v94
	v_fmac_f32_e32 v36, v156, v91
	v_fmac_f32_e32 v37, v158, v93
	v_add_f32_e32 v36, v36, v37
	v_add_f32_e32 v99, 0, v36
	v_mul_f32_e32 v44, v161, v96
	v_mul_f32_e32 v45, v163, v98
	v_fmac_f32_e32 v44, v160, v95
	v_fmac_f32_e32 v45, v162, v97
	v_add_f32_e32 v44, v44, v45
	v_add_f32_e32 v99, v99, v44
	v_mul_f32_e32 v36, v165, v104
	v_mul_f32_e32 v37, v167, v106
	v_fmac_f32_e32 v36, v164, v103
	v_fmac_f32_e32 v37, v166, v105
	v_add_f32_e32 v36, v36, v37
	v_add_f32_e32 v99, v99, v36
	v_mul_f32_e32 v44, v169, v21
	v_mul_f32_e32 v45, v171, v29
	v_fmac_f32_e32 v44, v168, v20
	v_fmac_f32_e32 v45, v170, v28
	v_add_f32_e32 v44, v44, v45
	v_add_f32_e32 v99, v99, v44
	v_mul_f32_e32 v36, v173, v92
	v_mul_f32_e32 v37, v175, v94
	v_fmac_f32_e32 v36, v172, v91
	v_fmac_f32_e32 v37, v174, v93
	v_add_f32_e32 v36, v36, v37
	v_add_f32_e32 v100, 0, v36
	v_mul_f32_e32 v44, v177, v96
	v_mul_f32_e32 v45, v179, v98
	v_fmac_f32_e32 v44, v176, v95
	v_fmac_f32_e32 v45, v178, v97
	v_add_f32_e32 v44, v44, v45
	v_add_f32_e32 v100, v100, v44
	v_mul_f32_e32 v36, v205, v104
	v_mul_f32_e32 v37, v207, v106
	v_fmac_f32_e32 v36, v204, v103
	v_fmac_f32_e32 v37, v206, v105
	v_add_f32_e32 v36, v36, v37
	v_add_f32_e32 v100, v100, v36
	v_mul_f32_e32 v44, v209, v21
	v_mul_f32_e32 v45, v211, v29
	v_fmac_f32_e32 v44, v208, v20
	v_fmac_f32_e32 v45, v210, v28
	v_add_f32_e32 v44, v44, v45
	v_add_f32_e32 v100, v100, v44
	v_mul_f32_e32 v36, v213, v92
	v_mul_f32_e32 v37, v215, v94
	v_fmac_f32_e32 v36, v212, v91
	v_fmac_f32_e32 v37, v214, v93
	v_add_f32_e32 v36, v36, v37
	v_add_f32_e32 v101, 0, v36
	v_mul_f32_e32 v44, v217, v96
	v_mul_f32_e32 v45, v219, v98
	v_fmac_f32_e32 v44, v216, v95
	v_fmac_f32_e32 v45, v218, v97
	v_add_f32_e32 v44, v44, v45
	v_add_f32_e32 v101, v101, v44
	v_mul_f32_e32 v36, v221, v104
	v_mul_f32_e32 v37, v223, v106
	v_fmac_f32_e32 v36, v220, v103
	v_fmac_f32_e32 v37, v222, v105
	v_add_f32_e32 v36, v36, v37
	v_add_f32_e32 v101, v101, v36
	v_mul_f32_e32 v44, v225, v21
	v_mul_f32_e32 v45, v227, v29
	v_fmac_f32_e32 v44, v224, v20
	v_fmac_f32_e32 v45, v226, v28
	v_add_f32_e32 v44, v44, v45
	v_add_f32_e32 v101, v101, v44
	v_mul_f32_e32 v36, v229, v92
	v_mul_f32_e32 v37, v231, v94
	v_fmac_f32_e32 v36, v228, v91
	v_fmac_f32_e32 v37, v230, v93
	v_add_f32_e32 v36, v36, v37
	v_add_f32_e32 v102, 0, v36
	v_mul_f32_e32 v44, v233, v96
	v_mul_f32_e32 v45, v235, v98
	v_fmac_f32_e32 v44, v232, v95
	v_fmac_f32_e32 v45, v234, v97
	v_add_f32_e32 v44, v44, v45
	v_add_f32_e32 v102, v102, v44
	v_mul_f32_e32 v36, v17, v104
	v_mul_f32_e32 v37, v19, v106
	v_fmac_f32_e32 v36, v16, v103
	v_fmac_f32_e32 v37, v18, v105
	v_add_f32_e32 v36, v36, v37
	v_add_f32_e32 v102, v102, v36
	v_mul_f32_e32 v44, v25, v21
	v_mul_f32_e32 v45, v27, v29
	v_fmac_f32_e32 v44, v24, v20
	v_fmac_f32_e32 v45, v26, v28
	v_add_f32_e32 v44, v44, v45
	v_add_f32_e32 v102, v102, v44
	v_mul_f32_e32 v36, v33, v92
	v_mul_f32_e32 v37, v35, v94
	v_fmac_f32_e32 v36, v32, v91
	v_fmac_f32_e32 v37, v34, v93
	v_add_f32_e32 v36, v36, v37
	v_add_f32_e32 v0, 0, v36
	v_mul_f32_e32 v44, v41, v96
	v_mul_f32_e32 v45, v43, v98
	v_fmac_f32_e32 v44, v40, v95
	v_fmac_f32_e32 v45, v42, v97
	v_add_f32_e32 v44, v44, v45
	v_add_f32_e32 v0, v0, v44
	v_mul_f32_e32 v36, v49, v104
	v_mul_f32_e32 v37, v51, v106
	v_fmac_f32_e32 v36, v48, v103
	v_fmac_f32_e32 v37, v50, v105
	v_add_f32_e32 v36, v36, v37
	v_add_f32_e32 v0, v0, v36
	v_mul_f32_e32 v44, v57, v21
	v_mul_f32_e32 v45, v59, v29
	v_fmac_f32_e32 v44, v56, v20
	v_fmac_f32_e32 v45, v58, v28
	v_add_f32_e32 v44, v44, v45
	v_add_f32_e32 v0, v0, v44
	v_cndmask_b32_e64 v2, v88, v100, s[2:3]
	ds_bpermute_b32 v2, v78, v2
	v_cndmask_b32_e64 v3, v89, v101, s[2:3]
	ds_bpermute_b32 v3, v78, v3
	v_cndmask_b32_e64 v84, v90, v102, s[2:3]
	ds_bpermute_b32 v84, v78, v84
	v_cndmask_b32_e64 v1, v100, v88, s[2:3]
	s_waitcnt lgkmcnt(2)
; __device__ __forceinline__ void phase_gates(ArgsRef a, const Tb tb, int l) {
;     ...
;         const bool b5 = (lane & 32) != 0, b4 = (lane & 16) != 0, b3 = (lane & 8) != 0;
;         float r4[4], q2[2];
; #pragma unroll
;         for (int j = 0; j < 4; ++j) { const float keep = b5 ? s8[j + 4] : s8[j], send = b5 ? s8[j] : s8[j + 4]; r4[j] = keep + __shfl_xor(send, 32); }
; #pragma unroll
;         for (int j = 0; j < 2; ++j) { const float keep = b4 ? r4[j + 2] : r4[j], send = b4 ? r4[j] : r4[j + 2]; q2[j] = keep + __shfl_xor(send, 16); }
;         float dv = (b3 ? q2[1] : q2[0]) + __shfl_xor(b3 ? q2[0] : q2[1], 8);
;         dv += __shfl_xor(dv, 4); dv += __shfl_xor(dv, 2); dv += __shfl_xor(dv, 1);
;         if ((lane & 7) == 0) {
;             const int j = lane >> 3;
;             const float v = rstd * (dv - mu * wg8[8192 + j]) + wg8[8192 + 8 + j];
;             float o;
;             if (j < 4) o = 1.f / (1.f + expf(-v));
;             else { const int h = j - 4; const float xx = v + a.in[10][l * 4 + h]; const float sp = fmaxf(xx, 0.f) + log1pf(expf(-fabsf(xx))); o = -expf(a.in[9][l * 4 + h]) * sp; }
;             gates[(size_t)t * 8 + (j < 4 ? 4 + j : j - 4)] = o;
	v_add_f32_e32 v1, v1, v2
	v_cndmask_b32_e64 v2, v101, v89, s[2:3]
	s_waitcnt lgkmcnt(1)
	v_add_f32_e32 v2, v2, v3
	v_cndmask_b32_e64 v3, v102, v90, s[2:3]
	s_waitcnt lgkmcnt(0)
	v_add_f32_e32 v3, v3, v84
	v_cndmask_b32_e64 v84, v0, v99, s[2:3]
	v_cndmask_b32_e64 v0, v99, v0, s[2:3]
	ds_bpermute_b32 v0, v78, v0
	s_waitcnt lgkmcnt(0)
	v_add_f32_e32 v0, v84, v0
	v_cndmask_b32_e64 v84, v3, v1, s[4:5]
	v_cndmask_b32_e64 v1, v1, v3, s[4:5]
	v_cndmask_b32_e64 v3, v0, v2, s[4:5]
	v_cndmask_b32_e64 v0, v2, v0, s[4:5]
	ds_bpermute_b32 v1, v79, v1
	ds_bpermute_b32 v0, v79, v0
	s_waitcnt lgkmcnt(1)
	v_add_f32_e32 v1, v84, v1
	s_waitcnt lgkmcnt(0)
	v_add_f32_e32 v0, v3, v0
	v_cndmask_b32_e64 v2, v0, v1, s[6:7]
	v_cndmask_b32_e64 v0, v1, v0, s[6:7]
	ds_bpermute_b32 v0, v80, v0
	s_waitcnt lgkmcnt(0)
	v_add_f32_e32 v0, v2, v0
	ds_bpermute_b32 v1, v81, v0
	s_waitcnt lgkmcnt(0)
	v_add_f32_e32 v0, v0, v1
	ds_bpermute_b32 v1, v82, v0
	s_waitcnt lgkmcnt(0)
	v_add_f32_e32 v0, v0, v1
	ds_bpermute_b32 v1, v83, v0
	s_and_saveexec_b64 s[24:25], s[8:9]
	s_cbranch_execz .LBB0_1189
	v_mov_b32_e32 v2, v52
	v_mov_b32_e32 v3, v53
	s_waitcnt lgkmcnt(0)
	v_add_f32_e32 v0, v0, v1
	v_mov_b32_e32 v1, v60
	v_fma_f32 v1, -v2, v1, v0
	v_mov_b32_e32 v0, v61
	v_fmac_f32_e32 v0, v3, v1
	s_and_saveexec_b64 s[26:27], s[10:11]
	s_xor_b64 s[26:27], exec, s[26:27]
	s_cbranch_execz .LBB0_1193
	v_mov_b32_e32 v1, v68
	s_mov_b32 s15, 0xbfb8aa3b
	v_add_f32_e32 v0, v0, v1
	v_mul_f32_e64 v1, |v0|, s15
	v_fma_f32 v2, |v0|, s15, -v1
	s_mov_b32 s15, 0xb2a5705f
	v_rndne_f32_e32 v3, v1
	v_fma_f32 v2, |v0|, s15, v2
	v_sub_f32_e32 v1, v1, v3
	v_add_f32_e32 v1, v1, v2
	v_exp_f32_e32 v1, v1
	v_cvt_i32_f32_e32 v2, v3
	v_cmp_ngt_f32_e64 vcc, |v0|, s31
	v_max_f32_e32 v94, 0, v0
	s_mov_b32 s15, 0x3f2aaaab
	v_ldexp_f32 v1, v1, v2
	v_cndmask_b32_e32 v1, 0, v1, vcc
	v_cmp_nlt_f32_e64 vcc, |v0|, s33
	s_nop 1
	v_cndmask_b32_e32 v95, v246, v1, vcc
	v_add_f32_e32 v2, 1.0, v95
	v_add_f32_e32 v0, -1.0, v2
	v_sub_f32_e32 v1, v0, v2
	v_add_f32_e32 v1, 1.0, v1
	v_sub_f32_e32 v0, v95, v0
	v_add_f32_e32 v3, v0, v1
	v_frexp_mant_f32_e32 v0, v2
	v_cmp_gt_f32_e32 vcc, s15, v0
	v_cvt_f64_f32_e32 v[0:1], v2
	v_frexp_exp_i32_f64_e32 v0, v[0:1]
	v_subbrev_co_u32_e32 v88, vcc, 0, v0, vcc
	v_sub_u32_e32 v0, 0, v88
	v_ldexp_f32 v1, v2, v0
	v_add_f32_e32 v2, -1.0, v1
	v_add_f32_e32 v84, 1.0, v1
	v_ldexp_f32 v0, v3, v0
	v_add_f32_e32 v3, 1.0, v2
	v_add_f32_e32 v85, -1.0, v84
	v_sub_f32_e32 v3, v1, v3
	v_sub_f32_e32 v1, v1, v85
	v_add_f32_e32 v3, v0, v3
	v_add_f32_e32 v0, v0, v1
	v_add_f32_e32 v89, v84, v0
	v_rcp_f32_e32 v91, v89
	v_sub_f32_e32 v1, v84, v89
	v_add_f32_e32 v90, v0, v1
	v_add_f32_e32 v1, v2, v3
	v_mul_f32_e32 v93, v1, v91
	v_sub_f32_e32 v0, v2, v1
	v_mul_f32_e32 v2, v89, v93
	v_fma_f32 v84, v93, v89, -v2
	v_fmac_f32_e32 v84, v93, v90
	v_add_f32_e32 v92, v3, v0
	v_add_f32_e32 v0, v2, v84
	v_sub_f32_e32 v3, v1, v0
	v_pk_add_f32 v[86:87], v[0:1], v[2:3] neg_lo:[0,1] neg_hi:[0,1]
	v_mov_b32_e32 v85, v0
	v_pk_add_f32 v[0:1], v[86:87], v[84:85] neg_lo:[0,1] neg_hi:[0,1]
	s_mov_b32 s15, 0x3f317218
	v_add_f32_e32 v1, v92, v1
	v_add_f32_e32 v0, v0, v1
	v_add_f32_e32 v1, v3, v0
	v_mul_f32_e32 v92, v91, v1
	v_mul_f32_e32 v2, v89, v92
	v_fma_f32 v84, v92, v89, -v2
	v_fmac_f32_e32 v84, v92, v90
	v_sub_f32_e32 v3, v3, v1
	v_add_f32_e32 v89, v0, v3
	v_add_f32_e32 v0, v2, v84
	v_sub_f32_e32 v3, v1, v0
	v_pk_add_f32 v[86:87], v[0:1], v[2:3] neg_lo:[0,1] neg_hi:[0,1]
	v_mov_b32_e32 v85, v0
	v_pk_add_f32 v[0:1], v[86:87], v[84:85] neg_lo:[0,1] neg_hi:[0,1]
	s_nop 0
	v_add_f32_e32 v1, v89, v1
	v_add_f32_e32 v0, v0, v1
	v_add_f32_e32 v1, v93, v92
	v_add_f32_e32 v0, v3, v0
	v_sub_f32_e32 v2, v1, v93
	v_mul_f32_e32 v0, v91, v0
	v_sub_f32_e32 v2, v92, v2
	v_add_f32_e32 v2, v2, v0
	v_add_f32_e32 v84, v1, v2
	v_mul_f32_e32 v85, v84, v84
	v_mov_b32_e32 v0, 0x3ecc95a3
	v_fmamk_f32 v0, v85, 0x3e9b6dac, v0
	v_fmaak_f32 v191, v85, v0, 0x3f2aaada
	v_cvt_f32_i32_e32 v0, v88
	v_sub_f32_e32 v1, v84, v1
	v_sub_f32_e32 v1, v2, v1
	v_ldexp_f32 v86, v1, 1
	v_mul_f32_e32 v1, v84, v85
	v_ldexp_f32 v3, v84, 1
	v_pk_mul_f32 v[84:85], v[0:1], v[190:191]
	s_nop 0
	v_fma_f32 v2, v0, s15, -v84
	v_fmac_f32_e32 v2, 0xb102e308, v0
	v_pk_add_f32 v[0:1], v[84:85], v[2:3]
	s_mov_b32 s15, 0x7f800000
	v_sub_f32_e32 v3, v1, v3
	v_sub_f32_e32 v3, v85, v3
	v_add_f32_e32 v87, v86, v3
	v_mov_b32_e32 v86, v84
	v_pk_add_f32 v[84:85], v[0:1], v[84:85] neg_lo:[0,1] neg_hi:[0,1]
	v_pk_add_f32 v[88:89], v[0:1], v[86:87]
	v_mov_b32_e32 v3, v0
	v_mov_b32_e32 v85, v89
	v_pk_add_f32 v[90:91], v[2:3], v[84:85] neg_lo:[0,1] neg_hi:[0,1]
	v_pk_add_f32 v[2:3], v[2:3], v[84:85]
	v_mov_b32_e32 v86, v87
	v_pk_add_f32 v[84:85], v[2:3], v[0:1] op_sel:[1,0] op_sel_hi:[0,1] neg_lo:[0,1] neg_hi:[0,1]
	v_pk_add_f32 v[92:93], v[88:89], v[84:85] op_sel_hi:[1,0] neg_lo:[0,1] neg_hi:[0,1]
	v_mov_b32_e32 v88, v89
	v_mov_b32_e32 v89, v3
	v_pk_mov_b32 v[84:85], v[0:1], v[84:85] op_sel:[1,0]
	v_mov_b32_e32 v87, v0
	v_pk_add_f32 v[84:85], v[88:89], v[84:85] neg_lo:[0,1] neg_hi:[0,1]
	v_mov_b32_e32 v92, v90
	v_pk_add_f32 v[0:1], v[86:87], v[84:85] neg_lo:[0,1] neg_hi:[0,1]
	v_mov_b32_e32 v91, v3
	v_pk_add_f32 v[84:85], v[92:93], v[0:1]
	v_cmp_neq_f32_e32 vcc, s15, v95
	v_pk_add_f32 v[86:87], v[84:85], v[84:85] op_sel:[0,1] op_sel_hi:[1,0]
	s_mov_b32 s15, 0x33800000
	v_pk_add_f32 v[2:3], v[2:3], v[86:87] op_sel:[1,0] op_sel_hi:[0,1]
	v_mov_b32_e32 v85, v2
	v_pk_add_f32 v[88:89], v[84:85], v[90:91] neg_lo:[0,1] neg_hi:[0,1]
	v_mov_b32_e32 v1, v86
	v_sub_f32_e32 v3, v84, v88
	v_pk_add_f32 v[0:1], v[0:1], v[88:89] neg_lo:[0,1] neg_hi:[0,1]
	v_sub_f32_e32 v3, v90, v3
	v_add_f32_e32 v0, v0, v3
	v_add_f32_e32 v0, v0, v1
	v_mov_b32_e32 v1, v69
	v_add_f32_e32 v0, v2, v0
	v_cndmask_b32_e32 v0, v246, v0, vcc
	v_cmp_lt_f32_e64 vcc, |v95|, s15
	v_mul_f32_e32 v2, 0x3fb8aa3b, v1
	v_rndne_f32_e32 v3, v2
	v_sub_f32_e32 v84, v2, v3
	v_fma_f32 v2, v1, s30, -v2
	v_fmac_f32_e32 v2, 0x32a5705f, v1
	v_add_f32_e32 v2, v84, v2
	v_exp_f32_e32 v2, v2
	v_cvt_i32_f32_e32 v3, v3
	v_cndmask_b32_e32 v0, v0, v95, vcc
	v_cmp_ngt_f32_e32 vcc, s34, v1
	v_add_f32_e32 v0, v94, v0
	v_ldexp_f32 v2, v2, v3
	v_cndmask_b32_e32 v2, 0, v2, vcc
	v_cmp_nlt_f32_e32 vcc, s35, v1
	s_nop 1
	v_cndmask_b32_e32 v1, v246, v2, vcc
	v_mul_f32_e64 v1, v0, -v1

; __device__ __forceinline__ unsigned pk2(float lo, float hi) { const f32x2_t v = {lo, hi}; const bf16x2_t b = __builtin_convertvector(v, bf16x2_t); return __builtin_bit_cast(unsigned, b); }
; template <int TYPE>
; __device__ __forceinline__ void attn_unit(const bf16_t* QK, const bf16_t* VT, bf16_t* O, int bh, int qb, float lam, const float* normg, float outscale, int tid, LAS unsigned char* lds) {
;     ...
; #pragma unroll
;         for (int mt = 0; mt < 2; ++mt)
; #pragma unroll
;             for (int i = 0; i < 16; ++i) ss += o1[mt][i] * o1[mt][i];
;     }
;     ss += __shfl_xor(ss, 32);
;     const float rn = rsqrtf(ss * (1.f / 64.f) + RMS_EPS_) * outscale;
;     bf16_t* orow = O + (tok0 + q0 + r) * 1024 + (TYPE ? 256 : 0) + hd * 64;
; #pragma unroll
;     for (int mt = 0; mt < 2; ++mt)
; #pragma unroll
;         for (int g4 = 0; g4 < 4; ++g4) {
;             const int dv0 = 32 * mt + 8 * g4 + 4 * h;
;             const f32x4 gg = *(const f32x4*)(normg + dv0);
;             u32x2 w; w.x = pk2(o1[mt][4 * g4 + 0] * rn * gg[0], o1[mt][4 * g4 + 1] * rn * gg[1]); w.y = pk2(o1[mt][4 * g4 + 2] * rn * gg[2], o1[mt][4 * g4 + 3] * rn * gg[3]);
;             *(u32x2*)(orow + dv0) = w;
;         }
.LBB0_1199:
	v_mul_f32_e32 v42, v17, v17
	v_fmac_f32_e32 v42, v16, v16
	v_fmac_f32_e32 v42, v18, v18
	v_fmac_f32_e32 v42, v19, v19
	v_fmac_f32_e32 v42, v20, v20
	v_fmac_f32_e32 v42, v21, v21
	v_fmac_f32_e32 v42, v22, v22
	v_fmac_f32_e32 v42, v23, v23
	v_fmac_f32_e32 v42, v24, v24
	v_fmac_f32_e32 v42, v25, v25
	v_fmac_f32_e32 v42, v26, v26
	v_fmac_f32_e32 v42, v27, v27
	v_fmac_f32_e32 v42, v28, v28
	v_fmac_f32_e32 v42, v29, v29
	v_fmac_f32_e32 v42, v30, v30
	v_fmac_f32_e32 v42, v31, v31
	v_fmac_f32_e32 v42, v0, v0
	v_fmac_f32_e32 v42, v1, v1
	v_fmac_f32_e32 v42, v2, v2
	v_fmac_f32_e32 v42, v3, v3
	v_fmac_f32_e32 v42, v4, v4
	v_fmac_f32_e32 v42, v5, v5
	v_pk_mul_f32 v[40:41], v[6:7], v[6:7]
	v_pk_mul_f32 v[38:39], v[8:9], v[8:9]
	v_add_f32_e32 v40, v40, v42
	v_add_f32_e32 v40, v41, v40
	v_add_f32_e32 v38, v38, v40
	v_pk_mul_f32 v[36:37], v[10:11], v[10:11]
	v_add_f32_e32 v38, v39, v38
	v_add_f32_e32 v36, v36, v38
	v_pk_mul_f32 v[34:35], v[12:13], v[12:13]
	v_add_f32_e32 v36, v37, v36
	v_add_f32_e32 v34, v34, v36
	global_load_dwordx4 v[36:39], v[214:215], off
	global_load_dwordx4 v[140:143], v[214:215], off offset:32
	global_load_dwordx4 v[144:147], v[214:215], off offset:64
	global_load_dwordx4 v[148:151], v[214:215], off offset:96
	global_load_dwordx4 v[152:155], v[214:215], off offset:128
	global_load_dwordx4 v[156:159], v[214:215], off offset:160
	global_load_dwordx4 v[160:163], v[214:215], off offset:192
	global_load_dwordx4 v[164:167], v[214:215], off offset:224
	v_pk_mul_f32 v[32:33], v[14:15], v[14:15]
	v_add_f32_e32 v34, v35, v34
	v_add_f32_e32 v32, v32, v34
	v_add_f32_e32 v32, v33, v32
	ds_bpermute_b32 v33, v191, v32
	s_mov_b32 s33, 0x800000
	v_readlane_b32 s36, v254, 50
	v_readlane_b32 s37, v254, 51
	v_readlane_b32 s72, v255, 10
	s_waitcnt lgkmcnt(0)
	v_add_f32_e32 v32, v32, v33
	v_fmamk_f32 v32, v32, 0x3c800000, v203
	v_cmp_gt_f32_e32 vcc, s33, v32
	v_mul_f32_e32 v33, 0x4b800000, v32
	v_lshl_add_u64 v[34:35], v[132:133], 1, s[36:37]
	v_cndmask_b32_e32 v32, v32, v33, vcc
	v_rsq_f32_e32 v32, v32
	v_readlane_b32 s36, v255, 8
	v_readlane_b32 s73, v255, 11
	v_readlane_b32 s37, v255, 9
	v_mul_f32_e32 v33, 0x45800000, v32
	v_cndmask_b32_e32 v32, v32, v33, vcc
	s_mov_b32 s37, s73
	v_pk_mul_f32 v[16:17], v[16:17], v[32:33] op_sel_hi:[1,0]
	v_pk_mul_f32 v[18:19], v[18:19], v[32:33] op_sel_hi:[1,0]
	v_lshl_add_u64 v[34:35], v[34:35], 0, s[36:37]
	v_mov_b32_e32 v219, v181
	v_lshl_add_u64 v[34:35], v[34:35], 0, v[218:219]
	v_pk_mul_f32 v[20:21], v[20:21], v[32:33] op_sel_hi:[1,0]
	v_pk_mul_f32 v[0:1], v[0:1], v[32:33] op_sel_hi:[1,0]
	v_pk_mul_f32 v[2:3], v[2:3], v[32:33] op_sel_hi:[1,0]
	v_pk_mul_f32 v[4:5], v[4:5], v[32:33] op_sel_hi:[1,0]
	v_readlane_b32 s36, v254, 36
	v_readlane_b32 s37, v254, 37
	v_readlane_b32 s33, v255, 2
	v_readlane_b32 s43, v255, 6
	v_readlane_b32 s42, v255, 4
	s_add_i32 s33, s33, s36
	s_add_i32 s43, s43, s36
	s_add_i32 s42, s42, s36
	v_readlane_b32 s36, v254, 19
	v_readlane_b32 s37, v254, 20
	s_mov_b32 s97, s49
	s_cmpk_gt_i32 s33, 0xff
	s_waitcnt vmcnt(0)
	v_pk_mul_f32 v[16:17], v[36:37], v[16:17]
	v_pk_mul_f32 v[18:19], v[38:39], v[18:19]
	v_cvt_pk_bf16_f32 v16, v16, v17
	v_cvt_pk_bf16_f32 v17, v18, v19
	global_store_dwordx2 v[34:35], v[16:17], off offset:512
	v_mov_b64_e32 v[16:17], v[140:141]
	v_mov_b64_e32 v[18:19], v[142:143]
	v_pk_mul_f32 v[16:17], v[16:17], v[20:21]
	v_pk_mul_f32 v[20:21], v[22:23], v[32:33] op_sel_hi:[1,0]
	v_cvt_pk_bf16_f32 v16, v16, v17
	v_pk_mul_f32 v[18:19], v[18:19], v[20:21]
	v_pk_mul_f32 v[20:21], v[24:25], v[32:33] op_sel_hi:[1,0]
	v_cvt_pk_bf16_f32 v17, v18, v19
	global_store_dwordx2 v[34:35], v[16:17], off offset:528
	v_mov_b64_e32 v[16:17], v[144:145]
	v_mov_b64_e32 v[18:19], v[146:147]
	v_pk_mul_f32 v[16:17], v[16:17], v[20:21]
	v_pk_mul_f32 v[20:21], v[26:27], v[32:33] op_sel_hi:[1,0]
	v_cvt_pk_bf16_f32 v16, v16, v17
	v_pk_mul_f32 v[18:19], v[18:19], v[20:21]
	v_pk_mul_f32 v[20:21], v[28:29], v[32:33] op_sel_hi:[1,0]
	v_cvt_pk_bf16_f32 v17, v18, v19
	global_store_dwordx2 v[34:35], v[16:17], off offset:544
	v_mov_b64_e32 v[16:17], v[148:149]
	v_mov_b64_e32 v[18:19], v[150:151]
	v_pk_mul_f32 v[16:17], v[16:17], v[20:21]
	v_pk_mul_f32 v[20:21], v[30:31], v[32:33] op_sel_hi:[1,0]
	v_cvt_pk_bf16_f32 v16, v16, v17
	v_pk_mul_f32 v[18:19], v[18:19], v[20:21]
	s_nop 0
	v_cvt_pk_bf16_f32 v17, v18, v19
	global_store_dwordx2 v[34:35], v[16:17], off offset:560
	v_mov_b64_e32 v[16:17], v[152:153]
	v_mov_b64_e32 v[18:19], v[154:155]
	v_pk_mul_f32 v[0:1], v[0:1], v[16:17]
	v_pk_mul_f32 v[2:3], v[2:3], v[18:19]
	v_cvt_pk_bf16_f32 v0, v0, v1
	v_cvt_pk_bf16_f32 v1, v2, v3
	global_store_dwordx2 v[34:35], v[0:1], off offset:576
	v_mov_b64_e32 v[0:1], v[156:157]
	v_mov_b64_e32 v[2:3], v[158:159]
	v_pk_mul_f32 v[0:1], v[4:5], v[0:1]
	v_pk_mul_f32 v[4:5], v[6:7], v[32:33] op_sel_hi:[1,0]
	v_cvt_pk_bf16_f32 v0, v0, v1
	v_pk_mul_f32 v[2:3], v[4:5], v[2:3]
	v_pk_mul_f32 v[4:5], v[8:9], v[32:33] op_sel_hi:[1,0]
	v_cvt_pk_bf16_f32 v1, v2, v3
	global_store_dwordx2 v[34:35], v[0:1], off offset:592
	v_mov_b64_e32 v[0:1], v[160:161]
	v_mov_b64_e32 v[2:3], v[162:163]
	v_pk_mul_f32 v[0:1], v[4:5], v[0:1]
	v_pk_mul_f32 v[4:5], v[10:11], v[32:33] op_sel_hi:[1,0]
	v_cvt_pk_bf16_f32 v0, v0, v1
	v_pk_mul_f32 v[2:3], v[4:5], v[2:3]
	v_pk_mul_f32 v[4:5], v[12:13], v[32:33] op_sel_hi:[1,0]
	v_cvt_pk_bf16_f32 v1, v2, v3
	global_store_dwordx2 v[34:35], v[0:1], off offset:608
	v_mov_b64_e32 v[0:1], v[164:165]
	v_mov_b64_e32 v[2:3], v[166:167]
	v_pk_mul_f32 v[0:1], v[4:5], v[0:1]
	v_pk_mul_f32 v[4:5], v[14:15], v[32:33] op_sel_hi:[1,0]
	v_cvt_pk_bf16_f32 v0, v0, v1
	v_pk_mul_f32 v[2:3], v[4:5], v[2:3]
	s_nop 0
	v_cvt_pk_bf16_f32 v1, v2, v3
	global_store_dwordx2 v[34:35], v[0:1], off offset:624
	s_load_dwordx2 s[48:49], s[36:37], 0x88
	s_cbranch_scc1 .LBB0_1255

; __device__ __forceinline__ unsigned pk2(float lo, float hi) { const f32x2_t v = {lo, hi}; const bf16x2_t b = __builtin_convertvector(v, bf16x2_t); return __builtin_bit_cast(unsigned, b); }
; template <int TYPE>
; __device__ __forceinline__ void attn_unit(const bf16_t* QK, const bf16_t* VT, bf16_t* O, int bh, int qb, float lam, const float* normg, float outscale, int tid, LAS unsigned char* lds) {
;     ...
;     float ss = 0.f;
;     if (TYPE == 0) {
;         l1 += __shfl_xor(l1, 32); l2 += __shfl_xor(l2, 32);
;         const float i1 = 1.f / l1, i2 = lam / l2;
; #pragma unroll
;         for (int mt = 0; mt < 2; ++mt)
; #pragma unroll
;             for (int i = 0; i < 16; ++i) { const float vv = o1[mt][i] * i1 - o2[mt][i] * i2; o1[mt][i] = vv; ss += vv * vv; }
;     ...
;     bf16_t* orow = O + (tok0 + q0 + r) * 1024 + (TYPE ? 256 : 0) + hd * 64;
; #pragma unroll
;     for (int mt = 0; mt < 2; ++mt)
; #pragma unroll
;         for (int g4 = 0; g4 < 4; ++g4) {
;             const int dv0 = 32 * mt + 8 * g4 + 4 * h;
;             const f32x4 gg = *(const f32x4*)(normg + dv0);
;             u32x2 w; w.x = pk2(o1[mt][4 * g4 + 0] * rn * gg[0], o1[mt][4 * g4 + 1] * rn * gg[1]); w.y = pk2(o1[mt][4 * g4 + 2] * rn * gg[2], o1[mt][4 * g4 + 3] * rn * gg[3]);
;             *(u32x2*)(orow + dv0) = w;
.LBB0_1237:
	ds_bpermute_b32 v66, v191, v219
	ds_bpermute_b32 v67, v191, v225
	v_lshlrev_b64 v[64:65], 10, v[226:227]
	s_mov_b32 s42, s48
	s_mov_b32 s43, s73
	s_waitcnt lgkmcnt(1)
	v_add_f32_e32 v66, v219, v66
	v_div_scale_f32 v68, s[36:37], v66, v66, 1.0
	v_rcp_f32_e32 v69, v68
	s_waitcnt lgkmcnt(0)
	v_add_f32_e32 v67, v225, v67
	v_mov_b32_e32 v219, v181
	s_mov_b32 s33, 0x800000
	v_fma_f32 v70, -v68, v69, 1.0
	v_fmac_f32_e32 v69, v70, v69
	v_div_scale_f32 v70, vcc, 1.0, v66, 1.0
	v_mul_f32_e32 v71, v70, v69
	v_fma_f32 v72, -v68, v71, v70
	v_fmac_f32_e32 v71, v72, v69
	v_fma_f32 v68, -v68, v71, v70
	v_div_fmas_f32 v68, v68, v69, v71
	v_div_fixup_f32 v66, v68, v66, 1.0
	v_div_scale_f32 v68, s[36:37], v67, v67, v197
	v_rcp_f32_e32 v69, v68
	v_readlane_b32 s36, v254, 50
	v_readlane_b32 s37, v254, 51
	v_mov_b32_e32 v225, v181
	v_fma_f32 v70, -v68, v69, 1.0
	v_fmac_f32_e32 v69, v70, v69
	v_div_scale_f32 v70, vcc, v197, v67, v197
	v_mul_f32_e32 v71, v70, v69
	v_fma_f32 v72, -v68, v71, v70
	v_fmac_f32_e32 v71, v72, v69
	v_fma_f32 v68, -v68, v71, v70
	v_div_fmas_f32 v68, v68, v69, v71
	v_div_fixup_f32 v68, v68, v67, v197
	v_pk_mul_f32 v[44:45], v[44:45], v[68:69] op_sel_hi:[1,0]
	v_pk_mul_f32 v[48:49], v[48:49], v[68:69] op_sel_hi:[1,0]
	v_pk_fma_f32 v[12:13], v[12:13], v[66:67], v[44:45] op_sel_hi:[1,0,1] neg_lo:[0,0,1] neg_hi:[0,0,1]
	v_pk_mul_f32 v[44:45], v[46:47], v[68:69] op_sel_hi:[1,0]
	v_pk_mul_f32 v[50:51], v[50:51], v[68:69] op_sel_hi:[1,0]
	v_pk_fma_f32 v[14:15], v[14:15], v[66:67], v[44:45] op_sel_hi:[1,0,1] neg_lo:[0,0,1] neg_hi:[0,0,1]
	v_lshl_add_u64 v[44:45], v[64:65], 1, s[36:37]
	v_lshl_add_u64 v[64:65], v[44:45], 0, s[42:43]
	global_load_dwordx4 v[44:47], v[212:213], off
	global_load_dwordx4 v[140:143], v[212:213], off offset:32
	global_load_dwordx4 v[144:147], v[212:213], off offset:64
	global_load_dwordx4 v[148:151], v[212:213], off offset:96
	global_load_dwordx4 v[152:155], v[212:213], off offset:128
	global_load_dwordx4 v[156:159], v[212:213], off offset:160
	global_load_dwordx4 v[160:163], v[212:213], off offset:192
	global_load_dwordx4 v[164:167], v[212:213], off offset:224
	v_pk_fma_f32 v[48:49], v[16:17], v[66:67], v[48:49] op_sel_hi:[1,0,1] neg_lo:[0,0,1] neg_hi:[0,0,1]
	v_pk_fma_f32 v[18:19], v[18:19], v[66:67], v[50:51] op_sel_hi:[1,0,1] neg_lo:[0,0,1] neg_hi:[0,0,1]
	v_pk_mul_f32 v[74:75], v[48:49], v[48:49]
	v_pk_mul_f32 v[50:51], v[18:19], v[18:19]
	v_lshl_add_u64 v[16:17], v[64:65], 0, v[218:219]
	v_pk_mul_f32 v[52:53], v[52:53], v[68:69] op_sel_hi:[1,0]
	v_add_f32_e32 v64, v74, v75
	v_pk_fma_f32 v[20:21], v[20:21], v[66:67], v[52:53] op_sel_hi:[1,0,1] neg_lo:[0,0,1] neg_hi:[0,0,1]
	v_add_f32_e32 v50, v50, v64
	v_pk_mul_f32 v[54:55], v[54:55], v[68:69] op_sel_hi:[1,0]
	v_pk_mul_f32 v[52:53], v[20:21], v[20:21]
	v_add_f32_e32 v50, v51, v50
	v_pk_fma_f32 v[22:23], v[22:23], v[66:67], v[54:55] op_sel_hi:[1,0,1] neg_lo:[0,0,1] neg_hi:[0,0,1]
	v_add_f32_e32 v50, v52, v50
	v_pk_mul_f32 v[54:55], v[22:23], v[22:23]
	v_pk_mul_f32 v[56:57], v[56:57], v[68:69] op_sel_hi:[1,0]
	v_add_f32_e32 v50, v53, v50
	v_pk_fma_f32 v[24:25], v[24:25], v[66:67], v[56:57] op_sel_hi:[1,0,1] neg_lo:[0,0,1] neg_hi:[0,0,1]
	v_add_f32_e32 v50, v54, v50
	v_pk_mul_f32 v[58:59], v[58:59], v[68:69] op_sel_hi:[1,0]
	v_pk_mul_f32 v[56:57], v[24:25], v[24:25]
	v_add_f32_e32 v50, v55, v50
	v_pk_fma_f32 v[26:27], v[26:27], v[66:67], v[58:59] op_sel_hi:[1,0,1] neg_lo:[0,0,1] neg_hi:[0,0,1]
	v_add_f32_e32 v50, v56, v50
	v_pk_mul_f32 v[58:59], v[26:27], v[26:27]
	v_pk_mul_f32 v[60:61], v[60:61], v[68:69] op_sel_hi:[1,0]
	v_add_f32_e32 v50, v57, v50
	v_pk_fma_f32 v[28:29], v[28:29], v[66:67], v[60:61] op_sel_hi:[1,0,1] neg_lo:[0,0,1] neg_hi:[0,0,1]
	v_add_f32_e32 v50, v58, v50
	v_pk_mul_f32 v[62:63], v[62:63], v[68:69] op_sel_hi:[1,0]
	v_pk_mul_f32 v[60:61], v[28:29], v[28:29]
	v_add_f32_e32 v50, v59, v50
	v_pk_fma_f32 v[30:31], v[30:31], v[66:67], v[62:63] op_sel_hi:[1,0,1] neg_lo:[0,0,1] neg_hi:[0,0,1]
	v_add_f32_e32 v50, v60, v50
	v_pk_mul_f32 v[62:63], v[30:31], v[30:31]
	v_pk_mul_f32 v[32:33], v[32:33], v[68:69] op_sel_hi:[1,0]
	v_add_f32_e32 v50, v61, v50
	v_pk_fma_f32 v[32:33], v[0:1], v[66:67], v[32:33] op_sel_hi:[1,0,1] neg_lo:[0,0,1] neg_hi:[0,0,1]
	v_add_f32_e32 v50, v62, v50
	v_pk_mul_f32 v[34:35], v[34:35], v[68:69] op_sel_hi:[1,0]
	v_pk_mul_f32 v[0:1], v[32:33], v[32:33]
	v_add_f32_e32 v50, v63, v50
	v_pk_fma_f32 v[34:35], v[2:3], v[66:67], v[34:35] op_sel_hi:[1,0,1] neg_lo:[0,0,1] neg_hi:[0,0,1]
	v_add_f32_e32 v0, v0, v50
	v_pk_mul_f32 v[2:3], v[34:35], v[34:35]
	v_pk_mul_f32 v[36:37], v[36:37], v[68:69] op_sel_hi:[1,0]
	v_add_f32_e32 v0, v1, v0
	v_pk_fma_f32 v[4:5], v[4:5], v[66:67], v[36:37] op_sel_hi:[1,0,1] neg_lo:[0,0,1] neg_hi:[0,0,1]
	v_add_f32_e32 v0, v2, v0
	v_pk_mul_f32 v[38:39], v[38:39], v[68:69] op_sel_hi:[1,0]
	v_pk_mul_f32 v[36:37], v[4:5], v[4:5]
	v_add_f32_e32 v0, v3, v0
	v_pk_fma_f32 v[6:7], v[6:7], v[66:67], v[38:39] op_sel_hi:[1,0,1] neg_lo:[0,0,1] neg_hi:[0,0,1]
	v_add_f32_e32 v0, v36, v0
	v_pk_mul_f32 v[38:39], v[6:7], v[6:7]
	v_pk_mul_f32 v[40:41], v[40:41], v[68:69] op_sel_hi:[1,0]
	v_add_f32_e32 v0, v37, v0
	v_pk_fma_f32 v[8:9], v[8:9], v[66:67], v[40:41] op_sel_hi:[1,0,1] neg_lo:[0,0,1] neg_hi:[0,0,1]
	v_add_f32_e32 v0, v38, v0
	v_pk_mul_f32 v[42:43], v[42:43], v[68:69] op_sel_hi:[1,0]
	v_pk_mul_f32 v[40:41], v[8:9], v[8:9]
	v_add_f32_e32 v0, v39, v0
	v_pk_fma_f32 v[10:11], v[10:11], v[66:67], v[42:43] op_sel_hi:[1,0,1] neg_lo:[0,0,1] neg_hi:[0,0,1]
	v_add_f32_e32 v0, v40, v0
	v_pk_mul_f32 v[42:43], v[10:11], v[10:11]
	v_add_f32_e32 v0, v41, v0
	v_add_f32_e32 v0, v42, v0
	v_pk_mul_f32 v[70:71], v[12:13], v[12:13]
	v_add_f32_e32 v0, v43, v0
	v_add_f32_e32 v0, v70, v0
	v_pk_mul_f32 v[72:73], v[14:15], v[14:15]
	v_add_f32_e32 v0, v71, v0
	v_add_f32_e32 v0, v72, v0
	v_add_f32_e32 v0, v73, v0
	ds_bpermute_b32 v1, v191, v0
	v_readlane_b32 s36, v254, 44
	v_readlane_b32 s37, v254, 45
	s_mov_b32 s49, s97
	v_mov_b32_e32 v136, 1.0
	s_waitcnt lgkmcnt(0)
; #define LAS __attribute__((address_space(3)))
; __device__ __forceinline__ int swap23(int x) { return (x & ~12) | ((x & 4) << 1) | ((x & 8) >> 1); }
; template <int TYPE>
; __device__ __forceinline__ void attn_unit(const bf16_t* QK, const bf16_t* VT, bf16_t* O, int bh, int qb, float lam, const float* normg, float outscale, int tid, LAS unsigned char* lds) {
;     const int wv = tid >> 6, lane = tid & 63, r = lane & 31, h = lane >> 5, b = bh >> 2, hd = bh & 3;
;     const int qg = qb * 8 + wv, q0 = qg * 32, ntile = (qb + 1) * 4;
;     const size_t tok0 = (size_t)b * SEQ_;
;     const bf16_t* qrow = QK + (tok0 + q0 + r) * 1024 + (TYPE ? 512 : 0) + hd * 64;
;     bf16x8 q[4];
; #pragma unroll
;     for (int s = 0; s < 4; ++s) q[s] = ldg8(qrow + 16 * s + 8 * h);
;     const bf16_t* kg = QK + (tok0 + (tid >> 3)) * 1024 + (TYPE ? 768 : 256) + hd * 64 + (tid & 7) * 8;
;     const bf16_t* vg = VT + ((size_t)(TYPE ? 16 : 0) + bh) * 64 * 4096 + (size_t)(tid >> 3) * 4096 + (tid & 7) * 8;
;     const unsigned lk = AT_K + (tid >> 3) * AT_ROW + (tid & 7) * 16, lv = AT_V + (tid >> 3) * AT_ROW + (tid & 7) * 16;
;     const unsigned fk = AT_K + swap23(r) * AT_ROW + 16 * h, fv = AT_V + r * AT_ROW + 16 * h;
;     f32x16 o1[2], o2[2];
; #pragma unroll
;     for (int i = 0; i < 16; ++i) { o1[0][i] = 0.f; o1[1][i] = 0.f; o2[0][i] = 0.f; o2[1][i] = 0.f; }
;     float m1 = -INFINITY, m2 = -INFINITY, l1 = 0.f, l2 = 0.f, run = 1.f;
;     {
;         const int tt = TYPE ? ntile - 1 : 0;
;         const u32x4 kx = *(const u32x4*)(kg + (size_t)tt * 64 * 1024), vx = *(const u32x4*)(vg + tt * 64);
;         *(LAS u32x4*)(lds + lk) = kx; *(LAS u32x4*)(lds + lv) = vx;
;     }
;     __syncthreads();
;     ...
;     ss += __shfl_xor(ss, 32);
;     const float rn = rsqrtf(ss * (1.f / 64.f) + RMS_EPS_) * outscale;
;     bf16_t* orow = O + (tok0 + q0 + r) * 1024 + (TYPE ? 256 : 0) + hd * 64;
; #pragma unroll
;     for (int mt = 0; mt < 2; ++mt)
; #pragma unroll
;         for (int g4 = 0; g4 < 4; ++g4) {
;             const int dv0 = 32 * mt + 8 * g4 + 4 * h;
;             const f32x4 gg = *(const f32x4*)(normg + dv0);
;             u32x2 w; w.x = pk2(o1[mt][4 * g4 + 0] * rn * gg[0], o1[mt][4 * g4 + 1] * rn * gg[1]); w.y = pk2(o1[mt][4 * g4 + 2] * rn * gg[2], o1[mt][4 * g4 + 3] * rn * gg[3]);
;             *(u32x2*)(orow + dv0) = w;
;         }
	v_add_f32_e32 v0, v0, v1
	v_fmamk_f32 v0, v0, 0x3c800000, v203
	v_cmp_gt_f32_e32 vcc, s33, v0
	v_mul_f32_e32 v1, 0x4b800000, v0
	s_sub_i32 s33, 15, s40
	v_cndmask_b32_e32 v0, v0, v1, vcc
	v_rsq_f32_e32 v0, v0
	v_lshl_add_u32 v137, s33, 3, v198
	s_lshl_b32 s38, s33, 2
	s_or_b32 s72, s38, 3
	v_mul_f32_e32 v1, 0x45800000, v0
	v_cndmask_b32_e32 v0, v0, v1, vcc
	v_mul_f32_e32 v36, v199, v0
	v_pk_mul_f32 v[0:1], v[48:49], v[36:37] op_sel_hi:[1,0]
	v_pk_mul_f32 v[2:3], v[18:19], v[36:37] op_sel_hi:[1,0]
	s_waitcnt vmcnt(0)
	v_pk_mul_f32 v[0:1], v[44:45], v[0:1]
	v_pk_mul_f32 v[2:3], v[46:47], v[2:3]
	v_cvt_pk_bf16_f32 v0, v0, v1
	v_cvt_pk_bf16_f32 v1, v2, v3
	global_store_dwordx2 v[16:17], v[0:1], off
	v_mov_b64_e32 v[0:1], v[140:141]
	v_mov_b64_e32 v[2:3], v[142:143]
	v_pk_mul_f32 v[18:19], v[20:21], v[36:37] op_sel_hi:[1,0]
	v_pk_mul_f32 v[4:5], v[4:5], v[36:37] op_sel_hi:[1,0]
	s_add_i32 s33, s38, 4
	s_mov_b32 s97, 1
	s_sub_i32 s46, s41, 64
	s_mov_b32 s47, 0
	v_pk_mul_f32 v[0:1], v[0:1], v[18:19]
	v_pk_mul_f32 v[18:19], v[22:23], v[36:37] op_sel_hi:[1,0]
	v_cvt_pk_bf16_f32 v0, v0, v1
	v_pk_mul_f32 v[2:3], v[2:3], v[18:19]
	v_pk_mul_f32 v[18:19], v[24:25], v[36:37] op_sel_hi:[1,0]
	v_cvt_pk_bf16_f32 v1, v2, v3
	global_store_dwordx2 v[16:17], v[0:1], off offset:16
	v_mov_b64_e32 v[0:1], v[144:145]
	v_mov_b64_e32 v[2:3], v[146:147]
	v_pk_mul_f32 v[0:1], v[0:1], v[18:19]
	v_pk_mul_f32 v[18:19], v[26:27], v[36:37] op_sel_hi:[1,0]
	v_cvt_pk_bf16_f32 v0, v0, v1
	v_pk_mul_f32 v[2:3], v[2:3], v[18:19]
	v_pk_mul_f32 v[18:19], v[28:29], v[36:37] op_sel_hi:[1,0]
	v_cvt_pk_bf16_f32 v1, v2, v3
	global_store_dwordx2 v[16:17], v[0:1], off offset:32
	v_mov_b64_e32 v[0:1], v[148:149]
	v_mov_b64_e32 v[2:3], v[150:151]
	v_pk_mul_f32 v[0:1], v[0:1], v[18:19]
	v_pk_mul_f32 v[18:19], v[30:31], v[36:37] op_sel_hi:[1,0]
	v_cvt_pk_bf16_f32 v0, v0, v1
	v_pk_mul_f32 v[2:3], v[2:3], v[18:19]
	v_pk_mul_f32 v[18:19], v[32:33], v[36:37] op_sel_hi:[1,0]
	v_cvt_pk_bf16_f32 v1, v2, v3
	global_store_dwordx2 v[16:17], v[0:1], off offset:48
	v_mov_b64_e32 v[0:1], v[152:153]
	v_mov_b64_e32 v[2:3], v[154:155]
	v_pk_mul_f32 v[0:1], v[0:1], v[18:19]
	v_pk_mul_f32 v[18:19], v[34:35], v[36:37] op_sel_hi:[1,0]
	v_cvt_pk_bf16_f32 v0, v0, v1
	v_pk_mul_f32 v[2:3], v[2:3], v[18:19]
	s_nop 0
	v_cvt_pk_bf16_f32 v1, v2, v3
	global_store_dwordx2 v[16:17], v[0:1], off offset:64
	v_mov_b64_e32 v[0:1], v[156:157]
	v_mov_b64_e32 v[2:3], v[158:159]
	v_pk_mul_f32 v[0:1], v[0:1], v[4:5]
	v_pk_mul_f32 v[4:5], v[6:7], v[36:37] op_sel_hi:[1,0]
	v_cvt_pk_bf16_f32 v0, v0, v1
	v_pk_mul_f32 v[2:3], v[2:3], v[4:5]
	v_pk_mul_f32 v[4:5], v[8:9], v[36:37] op_sel_hi:[1,0]
	v_cvt_pk_bf16_f32 v1, v2, v3
	global_store_dwordx2 v[16:17], v[0:1], off offset:80
	v_mov_b64_e32 v[0:1], v[160:161]
	v_mov_b64_e32 v[2:3], v[162:163]
	v_pk_mul_f32 v[0:1], v[0:1], v[4:5]
	v_pk_mul_f32 v[4:5], v[10:11], v[36:37] op_sel_hi:[1,0]
	v_cvt_pk_bf16_f32 v0, v0, v1
	v_pk_mul_f32 v[2:3], v[2:3], v[4:5]
	v_pk_mul_f32 v[4:5], v[12:13], v[36:37] op_sel_hi:[1,0]
	v_cvt_pk_bf16_f32 v1, v2, v3
	global_store_dwordx2 v[16:17], v[0:1], off offset:96
	v_mov_b64_e32 v[0:1], v[164:165]
	v_mov_b64_e32 v[2:3], v[166:167]
	v_pk_mul_f32 v[0:1], v[0:1], v[4:5]
	v_pk_mul_f32 v[4:5], v[14:15], v[36:37] op_sel_hi:[1,0]
	v_cvt_pk_bf16_f32 v0, v0, v1
	v_pk_mul_f32 v[2:3], v[2:3], v[4:5]
	s_nop 0
	v_cvt_pk_bf16_f32 v1, v2, v3
	global_store_dwordx2 v[16:17], v[0:1], off offset:112
	v_lshlrev_b32_e32 v0, 5, v137
	v_ashrrev_i32_e32 v1, 31, v0
	v_lshl_add_u64 v[0:1], v[0:1], 0, s[68:69]
	v_or_b32_e32 v0, v0, v200
	v_lshlrev_b64 v[132:133], 10, v[0:1]
	v_lshlrev_b64 v[0:1], 11, v[0:1]
	v_lshl_add_u64 v[0:1], s[36:37], 0, v[0:1]
	s_mov_b32 s36, s48
	v_lshl_add_u64 v[0:1], v[0:1], 0, s[42:43]
	v_writelane_b32 v255, s36, 8
	v_lshl_add_u64 v[0:1], v[0:1], 0, v[180:181]
	global_load_dwordx4 v[48:51], v[0:1], off offset:1024
	global_load_dwordx4 v[52:55], v[0:1], off offset:1056
	global_load_dwordx4 v[56:59], v[0:1], off offset:1088
	global_load_dwordx4 v[60:63], v[0:1], off offset:1120
	v_writelane_b32 v255, s37, 9
	v_lshl_add_u64 v[0:1], v[222:223], 0, v[224:225]
	s_mov_b64 s[36:37], 0x800000
	v_lshl_add_u64 v[134:135], v[0:1], 0, s[36:37]
	s_lshl_b64 s[36:37], s[72:73], 17
	v_lshl_add_u64 v[0:1], v[220:221], 0, s[36:37]
	s_lshl_b32 s72, s72, 7
	global_load_dwordx4 v[0:3], v[0:1], off offset:1536
	v_lshl_add_u64 v[4:5], v[134:135], 0, s[72:73]
	global_load_dwordx4 v[4:7], v[4:5], off
	s_mov_b32 s37, s73
	v_writelane_b32 v255, s36, 10
	v_mov_b32_e32 v16, 0
	v_mov_b32_e32 v17, v16
	v_writelane_b32 v255, s37, 11
	s_lshl_b32 s37, s40, 8
	s_sub_i32 s38, 0xf80, s37
	s_lshl_b32 s37, s40, 3
	s_sub_i32 s36, 62, s41
	s_sub_i32 s48, 0, s37
	v_mov_b32_e32 v18, v16
	v_mov_b32_e32 v19, v16
	v_mov_b32_e32 v20, v16
	v_mov_b32_e32 v21, v16
	v_mov_b32_e32 v22, v16
	v_mov_b32_e32 v23, v16
	v_mov_b32_e32 v24, v16
	v_mov_b32_e32 v25, v16
	s_waitcnt vmcnt(1)
	ds_write_b128 v252, v[0:3]
	s_waitcnt vmcnt(0)
	ds_write_b128 v252, v[4:7] offset:9216
	v_mov_b32_e32 v26, v16
	v_mov_b32_e32 v27, v16
	v_mov_b32_e32 v28, v16
	v_mov_b32_e32 v29, v16
	v_mov_b32_e32 v30, v16
	v_mov_b32_e32 v31, v16
	v_mov_b32_e32 v0, v16
	v_mov_b32_e32 v1, v16
	v_mov_b32_e32 v2, v16
	v_mov_b32_e32 v3, v16
	v_mov_b32_e32 v4, v16
	v_mov_b32_e32 v5, v16
	v_mov_b32_e32 v6, v16
	v_mov_b32_e32 v7, v16
	v_mov_b32_e32 v8, v16
	v_mov_b32_e32 v9, v16
	v_mov_b32_e32 v10, v16
	v_mov_b32_e32 v11, v16
	v_mov_b32_e32 v12, v16
	v_mov_b32_e32 v13, v16
	v_mov_b32_e32 v14, v16
	v_mov_b32_e32 v15, v16
	s_waitcnt lgkmcnt(0)
	s_barrier
	s_branch .LBB0_1239

; __device__ __forceinline__ unsigned xb_ld(unsigned* p)              { return __hip_atomic_load(p, __ATOMIC_RELAXED, __HIP_MEMORY_SCOPE_AGENT); }
; __device__ __forceinline__ void xcd_barrier_complete(unsigned* bar, unsigned x, unsigned& nloc, unsigned& nx) {
;     const unsigned G = gridDim.x * gridDim.y * gridDim.z;
;     unsigned sum, cnt, mine, sp = 0u;
;     for (;;) {
;         sum = 0u; cnt = 0u; mine = 0u;
; #pragma unroll
;         for (unsigned j = 0; j < 16; ++j) { const unsigned c = xb_ld(&bar[XB_XCNT(j)]); sum += c; cnt += (c > 0u) ? 1u : 0u; mine = (j == x) ? c : mine; }
;         if (sum == G) break;
;         __builtin_amdgcn_s_sleep(1);
;         if ((++sp & 255u) == 0u) { if (xb_ld(&bar[XB_TMO])) break; if (sp > XB_SPIN_CAP) { atomicAdd(&bar[XB_TMO], 1u); break; } }
;     }
;     nloc = mine > 0u ? mine : 1u; nx = cnt > 0u ? cnt : 1u;
; }
.LBB0_1658:
	v_readlane_b32 s4, v253, 8
	v_readlane_b32 s5, v253, 9
	s_mov_b64 s[6:7], -1
	s_waitcnt lgkmcnt(0)
	s_nop 4
	global_load_dword v0, v181, s[4:5] sc1
	global_load_dword v1, v181, s[4:5] offset:256 sc1
	global_load_dword v2, v181, s[4:5] offset:512 sc1
	global_load_dword v3, v181, s[4:5] offset:768 sc1
	global_load_dword v4, v181, s[4:5] offset:1024 sc1
	global_load_dword v5, v181, s[4:5] offset:1280 sc1
	global_load_dword v6, v181, s[4:5] offset:1536 sc1
	global_load_dword v7, v181, s[4:5] offset:1792 sc1
	global_load_dword v8, v181, s[4:5] offset:2048 sc1
	global_load_dword v9, v181, s[4:5] offset:2304 sc1
	global_load_dword v10, v181, s[4:5] offset:2560 sc1
	global_load_dword v11, v181, s[4:5] offset:2816 sc1
	global_load_dword v12, v181, s[4:5] offset:3072 sc1
	global_load_dword v13, v181, s[4:5] offset:3328 sc1
	global_load_dword v14, v181, s[4:5] offset:3584 sc1
	global_load_dword v15, v181, s[4:5] offset:3840 sc1
	s_nop 0
	s_mov_b64 s[4:5], -1
	s_waitcnt vmcnt(0)
	v_add_u32_e32 v16, v1, v0
	v_add_u32_e32 v16, v16, v2
	v_add_u32_e32 v16, v16, v3
	v_add_u32_e32 v16, v16, v4
	v_add_u32_e32 v16, v16, v5
	v_add_u32_e32 v16, v16, v6
	v_add_u32_e32 v16, v16, v7
	v_add_u32_e32 v16, v16, v8
	v_add_u32_e32 v16, v16, v9
	v_add_u32_e32 v16, v16, v10
	v_add_u32_e32 v16, v16, v11
	v_add_u32_e32 v16, v16, v12
	v_add_u32_e32 v16, v16, v13
	v_add_u32_e32 v16, v16, v14
	v_add_u32_e32 v16, v16, v15
	v_cmp_eq_u32_e32 vcc, s97, v16
	s_cbranch_vccnz .LBB0_1657
	s_and_b32 s4, s11, 0xff
	s_cmp_eq_u32 s4, 0
	s_mov_b64 s[4:5], -1
	s_mov_b64 s[8:9], -1
	s_sleep 1
	s_cbranch_scc0 .LBB0_1662
	v_readlane_b32 s4, v253, 6
	v_readlane_b32 s5, v253, 7
	s_nop 4
	global_load_dword v16, v181, s[4:5] sc1
	s_waitcnt vmcnt(0)
	v_cmp_eq_u32_e32 vcc, 0, v16
	s_cbranch_vccnz .LBB0_1664
	s_mov_b64 s[8:9], 0
	s_mov_b64 s[4:5], -1
